# residual GEMM epilogues: both 128-column halves of the residual row are loaded together (one wait per 16-row group instead of two)
# speedup vs baseline: 1.0057x; 1.0057x over previous
; DI void st8(bf16_t* p, const pg8::f32x4& v0, const pg8::f32x4& v1) { u32x4 w; w.x = cvtpk(v0[0], v0[1]); w.y = cvtpk(v0[2], v0[3]); w.z = cvtpk(v1[0], v1[1]); w.w = cvtpk(v1[2], v1[3]); *(u32x4*)p = w; }
;     DI void operator()(const pg8::f32x4 (&acc)[2][2][4][2], const pg8::Unit& u, int wr, int wc, int fr, int fq) const {
;         asm volatile("" : "+v"(fr), "+v"(fq));
;         const int b = u.pm / 9, seg = u.pm - b * 9, mrow = seg == 0 ? 32 : b;
;         const float* gbase = mods + (size_t)mrow * 6144 + gidx * 1024; const float* gpb = gp + (size_t)mrow * 1024;
; #pragma unroll
;         for (int ai = 0; ai < 2; ++ai)
; #pragma unroll
;             for (int m = 0; m < 4; ++m) { const int rit = ai * 128 + wr * 64 + m * 16 + fr; float ss = 0.f;
;                 const size_t roff = (seg == 0 ? (size_t)(b * TC + rit) * DM : (size_t)(b * SEQ + (seg - 1) * 256 + rit) * DM);
; #pragma unroll
;                 for (int bj = 0; bj < 2; ++bj) { const int col0 = u.pn * 256 + bj * 128 + wc * 32 + 8 * fq;
;                     float* p = (seg == 0 ? xc : out) + roff + col0; const float* q = (seg == 0 ? sc : sx) + roff + col0;
;                     const pg8::f32x4 g0 = *(const pg8::f32x4*)(gbase + col0), g1 = *(const pg8::f32x4*)(gbase + col0 + 4); pg8::f32x4 x0 = *(const pg8::f32x4*)q, x1 = *(const pg8::f32x4*)(q + 4);
;                     x0 += g0 * acc[ai][bj][m][0]; x1 += g1 * acc[ai][bj][m][1]; *(pg8::f32x4*)p = x0; *(pg8::f32x4*)(p + 4) = x1;
;                     if (emit) { const pg8::f32x4 p0 = *(const pg8::f32x4*)(gpb + col0), p1 = *(const pg8::f32x4*)(gpb + col0 + 4);
;                         ss += x0[0] * x0[0] + x0[1] * x0[1] + x0[2] * x0[2] + x0[3] * x0[3] + x1[0] * x1[0] + x1[1] * x1[1] + x1[2] * x1[2] + x1[3] * x1[3];
;                         st8(H + (size_t)(u.pm * 256 + rit) * 1024 + col0, x0 * p0, x1 * p1); }
.LBB0_878:
	s_mul_hi_i32 s2, s20, 0x38e38e39
	s_lshr_b32 s4, s2, 31
	s_ashr_i32 s2, s2, 1
	s_add_i32 s2, s2, s4
	s_mul_i32 s4, s2, -9
	s_add_i32 s4, s4, s20
	s_cmp_eq_u32 s4, 0
	s_cselect_b64 s[36:37], -1, 0
	s_and_b64 s[40:41], s[36:37], exec
	s_cselect_b32 s50, 32, s2
	s_ashr_i32 s51, s50, 31
	s_mul_i32 s7, s50, 0x6000
	s_mul_hi_i32 s5, s50, 0x6000
	s_add_u32 s7, s79, s7
	s_addc_u32 s5, s82, s5
	s_add_u32 s40, s7, 0x5000
	s_addc_u32 s41, s5, 0
	s_lshl_b32 s5, s6, 8
	v_mov_b32_e32 v158, v170
	v_mov_b32_e32 v159, v0
	s_or_b32 s5, s5, s44
	s_lshl_b32 s4, s4, 8
	v_lshl_add_u32 v160, v159, 3, s5
	s_lshl_b32 s5, s2, 11
	s_add_i32 s4, s5, s4
	s_lshl_b64 s[50:51], s[50:51], 12
	s_lshl_b32 s6, s20, 8
	s_addk_i32 s4, 0xff00
	s_lshl_b32 s2, s2, 8
	s_and_b64 s[20:21], s[36:37], exec
	v_add_u32_e32 v158, s39, v158
	s_cselect_b32 s2, s2, s4
	v_add_u32_e32 v162, s2, v158
	v_ashrrev_i32_e32 v163, 31, v162
	v_add_u32_e32 v164, s6, v158
	v_ashrrev_i32_e32 v165, 31, v164
	s_cselect_b32 s59, s38, s63
	s_cselect_b32 s58, s91, s62
	v_lshlrev_b64 v[162:163], 12, v[162:163]
	v_ashrrev_i32_e32 v161, 31, v160
	v_lshlrev_b64 v[168:169], 11, v[164:165]
	v_lshl_add_u64 v[162:163], s[58:59], 0, v[162:163]
	v_lshlrev_b64 v[164:165], 2, v[160:161]
	v_lshl_add_u64 v[166:167], v[162:163], 0, v[164:165]
	v_lshl_add_u64 v[164:165], s[40:41], 0, v[164:165]
	flat_load_dwordx4 v[208:211], v[164:165]
	flat_load_dwordx4 v[212:215], v[164:165] offset:16
	flat_load_dwordx4 v[198:201], v[166:167]
	flat_load_dwordx4 v[202:205], v[166:167] offset:16
	flat_load_dwordx4 v[240:243], v[166:167] offset:512
	flat_load_dwordx4 v[244:247], v[166:167] offset:528
	v_lshl_add_u64 v[152:153], v[138:139], 0, s[50:51]
	v_cndmask_b32_e64 v162, 0, 1, s[8:9]
	v_lshl_add_u64 v[168:169], s[64:65], 0, v[168:169]
	v_mov_b32_e32 v189, 0
	v_cmp_ne_u32_e64 s[36:37], 1, v162
	s_andn2_b64 vcc, exec, s[8:9]
	v_lshl_add_u64 v[162:163], v[160:161], 2, v[152:153]
	v_lshl_add_u64 v[168:169], v[160:161], 1, v[168:169]
	s_movk_i32 s33, 0x1000
	flat_load_dwordx4 v[216:219], v[164:165] offset:512
	flat_load_dwordx4 v[220:223], v[164:165] offset:528
	flat_load_dwordx4 v[224:227], v[162:163]
	flat_load_dwordx4 v[228:231], v[162:163] offset:16
	flat_load_dwordx4 v[232:235], v[162:163] offset:512
	flat_load_dwordx4 v[236:239], v[162:163] offset:528
	s_waitcnt vmcnt(0) lgkmcnt(0)
	v_pk_fma_f32 v[128:129], v[128:129], v[210:211], v[200:201]
	v_pk_fma_f32 v[126:127], v[126:127], v[208:209], v[198:199]
	v_pk_fma_f32 v[124:125], v[124:125], v[214:215], v[204:205]
	v_pk_fma_f32 v[122:123], v[122:123], v[212:213], v[202:203]
	flat_store_dwordx4 v[166:167], v[126:129]
	flat_store_dwordx4 v[166:167], v[122:125] offset:16
	s_cbranch_vccnz .LBB0_880
	v_pk_mul_f32 v[198:199], v[126:127], v[126:127]
	v_pk_mul_f32 v[152:153], v[128:129], v[128:129]
	v_add_f32_e32 v189, v198, v199
	v_add_f32_e32 v152, v152, v189
	v_pk_mul_f32 v[202:203], v[122:123], v[122:123]
	v_add_f32_e32 v152, v153, v152
	v_add_f32_e32 v152, v202, v152
	v_pk_mul_f32 v[200:201], v[124:125], v[124:125]
	v_add_f32_e32 v152, v203, v152
	v_add_f32_e32 v152, v200, v152
	v_add_f32_e32 v189, v201, v152
	v_pk_mul_f32 v[128:129], v[128:129], v[226:227]
	v_pk_mul_f32 v[152:153], v[124:125], v[230:231]
	v_pk_mul_f32 v[124:125], v[122:123], v[228:229]
	v_pk_mul_f32 v[126:127], v[126:127], v[224:225]
	s_nop 0
	v_cvt_pk_bf16_f32 v122, v126, v127
	v_cvt_pk_bf16_f32 v123, v128, v129
	v_cvt_pk_bf16_f32 v124, v124, v125
	v_cvt_pk_bf16_f32 v125, v152, v153
	flat_store_dwordx4 v[168:169], v[122:125]
.LBB0_880:
	s_nop 1
	v_add_u32_e32 v122, 0x80, v160
	v_ashrrev_i32_e32 v123, 31, v122
	v_lshl_add_u64 v[122:123], v[122:123], 2, s[40:41]
	s_and_b64 vcc, exec, s[36:37]
	v_pk_fma_f32 v[120:121], v[120:121], v[218:219], v[242:243]
	v_pk_fma_f32 v[118:119], v[118:119], v[216:217], v[240:241]
	v_pk_fma_f32 v[116:117], v[116:117], v[222:223], v[246:247]
	v_pk_fma_f32 v[114:115], v[114:115], v[220:221], v[244:245]
	flat_store_dwordx4 v[166:167], v[118:121] offset:512
	flat_store_dwordx4 v[166:167], v[114:117] offset:528
	s_cbranch_vccnz .LBB0_882
	v_pk_mul_f32 v[152:153], v[118:119], v[118:119]
	v_pk_mul_f32 v[128:129], v[120:121], v[120:121]
	v_add_f32_e32 v152, v152, v153
	v_add_f32_e32 v128, v128, v152
	v_pk_mul_f32 v[194:195], v[114:115], v[114:115]
	v_add_f32_e32 v128, v129, v128
	v_add_f32_e32 v128, v194, v128
	v_pk_mul_f32 v[166:167], v[116:117], v[116:117]
	v_add_f32_e32 v128, v195, v128
	v_add_f32_e32 v128, v166, v128
	v_add_f32_e32 v128, v167, v128
	v_add_f32_e32 v189, v189, v128
	v_pk_mul_f32 v[118:119], v[118:119], v[232:233]
	v_pk_mul_f32 v[124:125], v[116:117], v[238:239]
	v_pk_mul_f32 v[116:117], v[114:115], v[236:237]
	v_pk_mul_f32 v[120:121], v[120:121], v[234:235]
	v_cvt_pk_bf16_f32 v114, v118, v119
	s_nop 0
	v_cvt_pk_bf16_f32 v115, v120, v121
	v_cvt_pk_bf16_f32 v116, v116, v117
	v_cvt_pk_bf16_f32 v117, v124, v125
	flat_store_dwordx4 v[168:169], v[114:117] offset:256

; DI void st8(bf16_t* p, const pg8::f32x4& v0, const pg8::f32x4& v1) { u32x4 w; w.x = cvtpk(v0[0], v0[1]); w.y = cvtpk(v0[2], v0[3]); w.z = cvtpk(v1[0], v1[1]); w.w = cvtpk(v1[2], v1[3]); *(u32x4*)p = w; }
;     DI void operator()(const pg8::f32x4 (&acc)[2][2][4][2], const pg8::Unit& u, int wr, int wc, int fr, int fq) const {
;     ...
;             for (int m = 0; m < 4; ++m) { const int rit = ai * 128 + wr * 64 + m * 16 + fr; float ss = 0.f;
;                 const size_t roff = (seg == 0 ? (size_t)(b * TC + rit) * DM : (size_t)(b * SEQ + (seg - 1) * 256 + rit) * DM);
; #pragma unroll
;                 for (int bj = 0; bj < 2; ++bj) { const int col0 = u.pn * 256 + bj * 128 + wc * 32 + 8 * fq;
;                     float* p = (seg == 0 ? xc : out) + roff + col0; const float* q = (seg == 0 ? sc : sx) + roff + col0;
;                     const pg8::f32x4 g0 = *(const pg8::f32x4*)(gbase + col0), g1 = *(const pg8::f32x4*)(gbase + col0 + 4); pg8::f32x4 x0 = *(const pg8::f32x4*)q, x1 = *(const pg8::f32x4*)(q + 4);
;                     x0 += g0 * acc[ai][bj][m][0]; x1 += g1 * acc[ai][bj][m][1]; *(pg8::f32x4*)p = x0; *(pg8::f32x4*)(p + 4) = x1;
;                     if (emit) { const pg8::f32x4 p0 = *(const pg8::f32x4*)(gpb + col0), p1 = *(const pg8::f32x4*)(gpb + col0 + 4);
;                         ss += x0[0] * x0[0] + x0[1] * x0[1] + x0[2] * x0[2] + x0[3] * x0[3] + x1[0] * x1[0] + x1[1] * x1[1] + x1[2] * x1[2] + x1[3] * x1[3];
;                         st8(H + (size_t)(u.pm * 256 + rit) * 1024 + col0, x0 * p0, x1 * p1); }
.LBB0_886:
	v_add_u32_e32 v116, 16, v158
	v_add_u32_e32 v114, s2, v116
	s_waitcnt lgkmcnt(0)
	v_ashrrev_i32_e32 v115, 31, v114
	v_add_u32_e32 v116, s6, v116
	v_lshlrev_b64 v[114:115], 12, v[114:115]
	v_ashrrev_i32_e32 v117, 31, v116
	v_lshl_add_u64 v[114:115], s[58:59], 0, v[114:115]
	v_lshlrev_b64 v[120:121], 11, v[116:117]
	v_lshl_add_u64 v[114:115], v[160:161], 2, v[114:115]
	flat_load_dwordx4 v[166:169], v[114:115]
	flat_load_dwordx4 v[190:193], v[114:115] offset:16
	flat_load_dwordx4 v[240:243], v[114:115] offset:512
	flat_load_dwordx4 v[244:247], v[114:115] offset:528
	s_and_b64 vcc, exec, s[36:37]
	s_waitcnt vmcnt(0) lgkmcnt(0)
	v_pk_fma_f32 v[110:111], v[110:111], v[208:209], v[166:167]
	v_lshl_add_u64 v[116:117], s[64:65], 0, v[120:121]
	v_pk_fma_f32 v[112:113], v[112:113], v[210:211], v[168:169]
	v_pk_fma_f32 v[108:109], v[108:109], v[214:215], v[192:193]
	v_pk_fma_f32 v[106:107], v[106:107], v[212:213], v[190:191]
	v_mov_b32_e32 v118, 0
	v_lshl_add_u64 v[116:117], v[160:161], 1, v[116:117]
	flat_store_dwordx4 v[114:115], v[110:113]
	flat_store_dwordx4 v[114:115], v[106:109] offset:16
	s_cbranch_vccnz .LBB0_888
	v_pk_mul_f32 v[120:121], v[110:111], v[110:111]
	v_pk_mul_f32 v[118:119], v[112:113], v[112:113]
	v_add_f32_e32 v120, v120, v121
	v_add_f32_e32 v118, v118, v120
	v_pk_mul_f32 v[152:153], v[106:107], v[106:107]
	v_add_f32_e32 v118, v119, v118
	v_add_f32_e32 v118, v152, v118
	v_pk_mul_f32 v[128:129], v[108:109], v[108:109]
	v_add_f32_e32 v118, v153, v118
	v_add_f32_e32 v118, v128, v118
	v_add_f32_e32 v118, v129, v118
	v_pk_mul_f32 v[112:113], v[112:113], v[226:227]
	v_pk_mul_f32 v[120:121], v[108:109], v[230:231]
	v_pk_mul_f32 v[108:109], v[106:107], v[228:229]
	v_pk_mul_f32 v[110:111], v[110:111], v[224:225]
	s_nop 0
	v_cvt_pk_bf16_f32 v106, v110, v111
	v_cvt_pk_bf16_f32 v107, v112, v113
	v_cvt_pk_bf16_f32 v108, v108, v109
	v_cvt_pk_bf16_f32 v109, v120, v121
	flat_store_dwordx4 v[116:117], v[106:109]
.LBB0_888:
	s_nop 0
	s_and_b64 vcc, exec, s[36:37]
	v_pk_fma_f32 v[104:105], v[104:105], v[218:219], v[242:243]
	v_pk_fma_f32 v[102:103], v[102:103], v[216:217], v[240:241]
	v_pk_fma_f32 v[100:101], v[100:101], v[222:223], v[246:247]
	v_pk_fma_f32 v[98:99], v[98:99], v[220:221], v[244:245]
	flat_store_dwordx4 v[114:115], v[102:105] offset:512
	flat_store_dwordx4 v[114:115], v[98:101] offset:528
	s_cbranch_vccnz .LBB0_890
	v_pk_mul_f32 v[120:121], v[102:103], v[102:103]
	v_pk_mul_f32 v[114:115], v[104:105], v[104:105]
	v_add_f32_e32 v119, v120, v121
	v_add_f32_e32 v114, v114, v119
	v_pk_mul_f32 v[126:127], v[98:99], v[98:99]
	v_add_f32_e32 v114, v115, v114
	v_add_f32_e32 v114, v126, v114
	v_pk_mul_f32 v[124:125], v[100:101], v[100:101]
	v_add_f32_e32 v114, v127, v114
	v_add_f32_e32 v114, v124, v114
	v_add_f32_e32 v114, v125, v114
	v_add_f32_e32 v118, v118, v114
	v_pk_mul_f32 v[102:103], v[102:103], v[232:233]
	v_pk_mul_f32 v[106:107], v[100:101], v[238:239]
	v_pk_mul_f32 v[100:101], v[98:99], v[236:237]
	v_pk_mul_f32 v[104:105], v[104:105], v[234:235]
	v_cvt_pk_bf16_f32 v98, v102, v103
	s_nop 0
	v_cvt_pk_bf16_f32 v99, v104, v105
	v_cvt_pk_bf16_f32 v100, v100, v101
	v_cvt_pk_bf16_f32 v101, v106, v107
	flat_store_dwordx4 v[116:117], v[98:101] offset:256

; DI void st8(bf16_t* p, const pg8::f32x4& v0, const pg8::f32x4& v1) { u32x4 w; w.x = cvtpk(v0[0], v0[1]); w.y = cvtpk(v0[2], v0[3]); w.z = cvtpk(v1[0], v1[1]); w.w = cvtpk(v1[2], v1[3]); *(u32x4*)p = w; }
;     DI void operator()(const pg8::f32x4 (&acc)[2][2][4][2], const pg8::Unit& u, int wr, int wc, int fr, int fq) const {
;     ...
;             for (int m = 0; m < 4; ++m) { const int rit = ai * 128 + wr * 64 + m * 16 + fr; float ss = 0.f;
;                 const size_t roff = (seg == 0 ? (size_t)(b * TC + rit) * DM : (size_t)(b * SEQ + (seg - 1) * 256 + rit) * DM);
; #pragma unroll
;                 for (int bj = 0; bj < 2; ++bj) { const int col0 = u.pn * 256 + bj * 128 + wc * 32 + 8 * fq;
;                     float* p = (seg == 0 ? xc : out) + roff + col0; const float* q = (seg == 0 ? sc : sx) + roff + col0;
;                     const pg8::f32x4 g0 = *(const pg8::f32x4*)(gbase + col0), g1 = *(const pg8::f32x4*)(gbase + col0 + 4); pg8::f32x4 x0 = *(const pg8::f32x4*)q, x1 = *(const pg8::f32x4*)(q + 4);
;                     x0 += g0 * acc[ai][bj][m][0]; x1 += g1 * acc[ai][bj][m][1]; *(pg8::f32x4*)p = x0; *(pg8::f32x4*)(p + 4) = x1;
;                     if (emit) { const pg8::f32x4 p0 = *(const pg8::f32x4*)(gpb + col0), p1 = *(const pg8::f32x4*)(gpb + col0 + 4);
;                         ss += x0[0] * x0[0] + x0[1] * x0[1] + x0[2] * x0[2] + x0[3] * x0[3] + x1[0] * x1[0] + x1[1] * x1[1] + x1[2] * x1[2] + x1[3] * x1[3];
;                         st8(H + (size_t)(u.pm * 256 + rit) * 1024 + col0, x0 * p0, x1 * p1); }
.LBB0_894:
	v_add_u32_e32 v100, 32, v158
	v_add_u32_e32 v98, s2, v100
	s_waitcnt lgkmcnt(0)
	v_ashrrev_i32_e32 v99, 31, v98
	v_add_u32_e32 v100, s6, v100
	v_lshlrev_b64 v[98:99], 12, v[98:99]
	v_ashrrev_i32_e32 v101, 31, v100
	v_lshl_add_u64 v[98:99], s[58:59], 0, v[98:99]
	v_lshlrev_b64 v[116:117], 11, v[100:101]
	v_lshl_add_u64 v[98:99], v[160:161], 2, v[98:99]
	flat_load_dwordx4 v[108:111], v[98:99]
	flat_load_dwordx4 v[112:115], v[98:99] offset:16
	flat_load_dwordx4 v[240:243], v[98:99] offset:512
	flat_load_dwordx4 v[244:247], v[98:99] offset:528
	s_and_b64 vcc, exec, s[36:37]
	s_waitcnt vmcnt(0) lgkmcnt(0)
	v_pk_fma_f32 v[94:95], v[94:95], v[208:209], v[108:109]
	v_lshl_add_u64 v[100:101], s[64:65], 0, v[116:117]
	v_pk_fma_f32 v[96:97], v[96:97], v[210:211], v[110:111]
	v_pk_fma_f32 v[92:93], v[92:93], v[214:215], v[114:115]
	v_pk_fma_f32 v[90:91], v[90:91], v[212:213], v[112:113]
	v_mov_b32_e32 v102, 0
	v_lshl_add_u64 v[100:101], v[160:161], 1, v[100:101]
	flat_store_dwordx4 v[98:99], v[94:97]
	flat_store_dwordx4 v[98:99], v[90:93] offset:16
	s_cbranch_vccnz .LBB0_896
	v_pk_mul_f32 v[112:113], v[94:95], v[94:95]
	v_pk_mul_f32 v[102:103], v[96:97], v[96:97]
	v_add_f32_e32 v112, v112, v113
	v_add_f32_e32 v102, v102, v112
	v_pk_mul_f32 v[116:117], v[90:91], v[90:91]
	v_add_f32_e32 v102, v103, v102
	v_add_f32_e32 v102, v116, v102
	v_pk_mul_f32 v[114:115], v[92:93], v[92:93]
	v_add_f32_e32 v102, v117, v102
	v_add_f32_e32 v102, v114, v102
	v_add_f32_e32 v102, v115, v102
	v_pk_mul_f32 v[94:95], v[94:95], v[224:225]
	v_pk_mul_f32 v[104:105], v[92:93], v[230:231]
	v_pk_mul_f32 v[92:93], v[90:91], v[228:229]
	v_pk_mul_f32 v[96:97], v[96:97], v[226:227]
	v_cvt_pk_bf16_f32 v90, v94, v95
	s_nop 0
	v_cvt_pk_bf16_f32 v91, v96, v97
	v_cvt_pk_bf16_f32 v92, v92, v93
	v_cvt_pk_bf16_f32 v93, v104, v105
	flat_store_dwordx4 v[100:101], v[90:93]
.LBB0_896:
	s_nop 0
	s_and_b64 vcc, exec, s[36:37]
	v_pk_fma_f32 v[88:89], v[88:89], v[218:219], v[242:243]
	v_pk_fma_f32 v[86:87], v[86:87], v[216:217], v[240:241]
	v_pk_fma_f32 v[84:85], v[84:85], v[222:223], v[246:247]
	v_pk_fma_f32 v[82:83], v[82:83], v[220:221], v[244:245]
	flat_store_dwordx4 v[98:99], v[86:89] offset:512
	flat_store_dwordx4 v[98:99], v[82:85] offset:528
	s_cbranch_vccnz .LBB0_898
	v_pk_mul_f32 v[104:105], v[86:87], v[86:87]
	v_pk_mul_f32 v[98:99], v[88:89], v[88:89]
	v_add_f32_e32 v103, v104, v105
	v_add_f32_e32 v98, v98, v103
	v_pk_mul_f32 v[108:109], v[82:83], v[82:83]
	v_add_f32_e32 v98, v99, v98
	v_add_f32_e32 v98, v108, v98
	v_pk_mul_f32 v[106:107], v[84:85], v[84:85]
	v_add_f32_e32 v98, v109, v98
	v_add_f32_e32 v98, v106, v98
	v_add_f32_e32 v98, v107, v98
	v_add_f32_e32 v102, v102, v98
	v_pk_mul_f32 v[86:87], v[86:87], v[232:233]
	v_pk_mul_f32 v[90:91], v[84:85], v[238:239]
	v_pk_mul_f32 v[84:85], v[82:83], v[236:237]
	v_pk_mul_f32 v[88:89], v[88:89], v[234:235]
	v_cvt_pk_bf16_f32 v82, v86, v87
	s_nop 0
	v_cvt_pk_bf16_f32 v83, v88, v89
	v_cvt_pk_bf16_f32 v84, v84, v85
	v_cvt_pk_bf16_f32 v85, v90, v91
	flat_store_dwordx4 v[100:101], v[82:85] offset:256

; DI void st8(bf16_t* p, const pg8::f32x4& v0, const pg8::f32x4& v1) { u32x4 w; w.x = cvtpk(v0[0], v0[1]); w.y = cvtpk(v0[2], v0[3]); w.z = cvtpk(v1[0], v1[1]); w.w = cvtpk(v1[2], v1[3]); *(u32x4*)p = w; }
;     DI void operator()(const pg8::f32x4 (&acc)[2][2][4][2], const pg8::Unit& u, int wr, int wc, int fr, int fq) const {
;     ...
;             for (int m = 0; m < 4; ++m) { const int rit = ai * 128 + wr * 64 + m * 16 + fr; float ss = 0.f;
;                 const size_t roff = (seg == 0 ? (size_t)(b * TC + rit) * DM : (size_t)(b * SEQ + (seg - 1) * 256 + rit) * DM);
; #pragma unroll
;                 for (int bj = 0; bj < 2; ++bj) { const int col0 = u.pn * 256 + bj * 128 + wc * 32 + 8 * fq;
;                     float* p = (seg == 0 ? xc : out) + roff + col0; const float* q = (seg == 0 ? sc : sx) + roff + col0;
;                     const pg8::f32x4 g0 = *(const pg8::f32x4*)(gbase + col0), g1 = *(const pg8::f32x4*)(gbase + col0 + 4); pg8::f32x4 x0 = *(const pg8::f32x4*)q, x1 = *(const pg8::f32x4*)(q + 4);
;                     x0 += g0 * acc[ai][bj][m][0]; x1 += g1 * acc[ai][bj][m][1]; *(pg8::f32x4*)p = x0; *(pg8::f32x4*)(p + 4) = x1;
;                     if (emit) { const pg8::f32x4 p0 = *(const pg8::f32x4*)(gpb + col0), p1 = *(const pg8::f32x4*)(gpb + col0 + 4);
;                         ss += x0[0] * x0[0] + x0[1] * x0[1] + x0[2] * x0[2] + x0[3] * x0[3] + x1[0] * x1[0] + x1[1] * x1[1] + x1[2] * x1[2] + x1[3] * x1[3];
;                         st8(H + (size_t)(u.pm * 256 + rit) * 1024 + col0, x0 * p0, x1 * p1); }
.LBB0_902:
	v_add_u32_e32 v84, 48, v158
	v_add_u32_e32 v82, s2, v84
	s_waitcnt lgkmcnt(0)
	v_ashrrev_i32_e32 v83, 31, v82
	v_add_u32_e32 v84, s6, v84
	v_lshlrev_b64 v[82:83], 12, v[82:83]
	v_ashrrev_i32_e32 v85, 31, v84
	v_lshl_add_u64 v[82:83], s[58:59], 0, v[82:83]
	v_lshlrev_b64 v[100:101], 11, v[84:85]
	v_lshl_add_u64 v[82:83], v[160:161], 2, v[82:83]
	flat_load_dwordx4 v[92:95], v[82:83]
	flat_load_dwordx4 v[96:99], v[82:83] offset:16
	flat_load_dwordx4 v[240:243], v[82:83] offset:512
	flat_load_dwordx4 v[244:247], v[82:83] offset:528
	s_and_b64 vcc, exec, s[36:37]
	s_waitcnt vmcnt(0) lgkmcnt(0)
	v_pk_fma_f32 v[78:79], v[78:79], v[208:209], v[92:93]
	v_lshl_add_u64 v[84:85], s[64:65], 0, v[100:101]
	v_pk_fma_f32 v[80:81], v[80:81], v[210:211], v[94:95]
	v_pk_fma_f32 v[76:77], v[76:77], v[214:215], v[98:99]
	v_pk_fma_f32 v[74:75], v[74:75], v[212:213], v[96:97]
	v_mov_b32_e32 v86, 0
	v_lshl_add_u64 v[84:85], v[160:161], 1, v[84:85]
	flat_store_dwordx4 v[82:83], v[78:81]
	flat_store_dwordx4 v[82:83], v[74:77] offset:16
	s_cbranch_vccnz .LBB0_904
	v_pk_mul_f32 v[96:97], v[78:79], v[78:79]
	v_pk_mul_f32 v[86:87], v[80:81], v[80:81]
	v_add_f32_e32 v96, v96, v97
	v_add_f32_e32 v86, v86, v96
	v_pk_mul_f32 v[100:101], v[74:75], v[74:75]
	v_add_f32_e32 v86, v87, v86
	v_add_f32_e32 v86, v100, v86
	v_pk_mul_f32 v[98:99], v[76:77], v[76:77]
	v_add_f32_e32 v86, v101, v86
	v_add_f32_e32 v86, v98, v86
	v_add_f32_e32 v86, v99, v86
	v_pk_mul_f32 v[78:79], v[78:79], v[224:225]
	v_pk_mul_f32 v[88:89], v[76:77], v[230:231]
	v_pk_mul_f32 v[76:77], v[74:75], v[228:229]
	v_pk_mul_f32 v[80:81], v[80:81], v[226:227]
	v_cvt_pk_bf16_f32 v74, v78, v79
	s_nop 0
	v_cvt_pk_bf16_f32 v75, v80, v81
	v_cvt_pk_bf16_f32 v76, v76, v77
	v_cvt_pk_bf16_f32 v77, v88, v89
	flat_store_dwordx4 v[84:85], v[74:77]
.LBB0_904:
	s_nop 0
	s_and_b64 vcc, exec, s[36:37]
	v_pk_fma_f32 v[72:73], v[72:73], v[218:219], v[242:243]
	v_pk_fma_f32 v[70:71], v[70:71], v[216:217], v[240:241]
	v_pk_fma_f32 v[68:69], v[68:69], v[222:223], v[246:247]
	v_pk_fma_f32 v[66:67], v[66:67], v[220:221], v[244:245]
	flat_store_dwordx4 v[82:83], v[70:73] offset:512
	flat_store_dwordx4 v[82:83], v[66:69] offset:528
	s_cbranch_vccnz .LBB0_906
	v_pk_mul_f32 v[88:89], v[70:71], v[70:71]
	v_pk_mul_f32 v[82:83], v[72:73], v[72:73]
	v_add_f32_e32 v87, v88, v89
	v_add_f32_e32 v82, v82, v87
	v_pk_mul_f32 v[92:93], v[66:67], v[66:67]
	v_add_f32_e32 v82, v83, v82
	v_add_f32_e32 v82, v92, v82
	v_pk_mul_f32 v[90:91], v[68:69], v[68:69]
	v_add_f32_e32 v82, v93, v82
	v_add_f32_e32 v82, v90, v82
	v_add_f32_e32 v82, v91, v82
	v_add_f32_e32 v86, v86, v82
	v_pk_mul_f32 v[70:71], v[70:71], v[232:233]
	v_pk_mul_f32 v[74:75], v[68:69], v[238:239]
	v_pk_mul_f32 v[68:69], v[66:67], v[236:237]
	v_pk_mul_f32 v[72:73], v[72:73], v[234:235]
	v_cvt_pk_bf16_f32 v66, v70, v71
	s_nop 0
	v_cvt_pk_bf16_f32 v67, v72, v73
	v_cvt_pk_bf16_f32 v68, v68, v69
	v_cvt_pk_bf16_f32 v69, v74, v75
	flat_store_dwordx4 v[84:85], v[66:69] offset:256

; DI void st8(bf16_t* p, const pg8::f32x4& v0, const pg8::f32x4& v1) { u32x4 w; w.x = cvtpk(v0[0], v0[1]); w.y = cvtpk(v0[2], v0[3]); w.z = cvtpk(v1[0], v1[1]); w.w = cvtpk(v1[2], v1[3]); *(u32x4*)p = w; }
;     DI void operator()(const pg8::f32x4 (&acc)[2][2][4][2], const pg8::Unit& u, int wr, int wc, int fr, int fq) const {
;     ...
;             for (int m = 0; m < 4; ++m) { const int rit = ai * 128 + wr * 64 + m * 16 + fr; float ss = 0.f;
;                 const size_t roff = (seg == 0 ? (size_t)(b * TC + rit) * DM : (size_t)(b * SEQ + (seg - 1) * 256 + rit) * DM);
; #pragma unroll
;                 for (int bj = 0; bj < 2; ++bj) { const int col0 = u.pn * 256 + bj * 128 + wc * 32 + 8 * fq;
;                     float* p = (seg == 0 ? xc : out) + roff + col0; const float* q = (seg == 0 ? sc : sx) + roff + col0;
;                     const pg8::f32x4 g0 = *(const pg8::f32x4*)(gbase + col0), g1 = *(const pg8::f32x4*)(gbase + col0 + 4); pg8::f32x4 x0 = *(const pg8::f32x4*)q, x1 = *(const pg8::f32x4*)(q + 4);
;                     x0 += g0 * acc[ai][bj][m][0]; x1 += g1 * acc[ai][bj][m][1]; *(pg8::f32x4*)p = x0; *(pg8::f32x4*)(p + 4) = x1;
;                     if (emit) { const pg8::f32x4 p0 = *(const pg8::f32x4*)(gpb + col0), p1 = *(const pg8::f32x4*)(gpb + col0 + 4);
;                         ss += x0[0] * x0[0] + x0[1] * x0[1] + x0[2] * x0[2] + x0[3] * x0[3] + x1[0] * x1[0] + x1[1] * x1[1] + x1[2] * x1[2] + x1[3] * x1[3];
;                         st8(H + (size_t)(u.pm * 256 + rit) * 1024 + col0, x0 * p0, x1 * p1); }
.LBB0_910:
	v_add_u32_e32 v68, 0x80, v158
	v_add_u32_e32 v66, s2, v68
	s_waitcnt lgkmcnt(0)
	v_ashrrev_i32_e32 v67, 31, v66
	v_add_u32_e32 v68, s6, v68
	v_lshlrev_b64 v[66:67], 12, v[66:67]
	v_ashrrev_i32_e32 v69, 31, v68
	v_lshl_add_u64 v[66:67], s[58:59], 0, v[66:67]
	v_lshlrev_b64 v[84:85], 11, v[68:69]
	v_lshl_add_u64 v[66:67], v[160:161], 2, v[66:67]
	flat_load_dwordx4 v[76:79], v[66:67]
	flat_load_dwordx4 v[80:83], v[66:67] offset:16
	flat_load_dwordx4 v[240:243], v[66:67] offset:512
	flat_load_dwordx4 v[244:247], v[66:67] offset:528
	s_and_b64 vcc, exec, s[36:37]
	s_waitcnt vmcnt(0) lgkmcnt(0)
	v_pk_fma_f32 v[62:63], v[62:63], v[208:209], v[76:77]
	v_lshl_add_u64 v[68:69], s[64:65], 0, v[84:85]
	v_pk_fma_f32 v[64:65], v[64:65], v[210:211], v[78:79]
	v_pk_fma_f32 v[60:61], v[60:61], v[214:215], v[82:83]
	v_pk_fma_f32 v[58:59], v[58:59], v[212:213], v[80:81]
	v_mov_b32_e32 v70, 0
	v_lshl_add_u64 v[68:69], v[160:161], 1, v[68:69]
	flat_store_dwordx4 v[66:67], v[62:65]
	flat_store_dwordx4 v[66:67], v[58:61] offset:16
	s_cbranch_vccnz .LBB0_912
	v_pk_mul_f32 v[80:81], v[62:63], v[62:63]
	v_pk_mul_f32 v[70:71], v[64:65], v[64:65]
	v_add_f32_e32 v80, v80, v81
	v_add_f32_e32 v70, v70, v80
	v_pk_mul_f32 v[84:85], v[58:59], v[58:59]
	v_add_f32_e32 v70, v71, v70
	v_add_f32_e32 v70, v84, v70
	v_pk_mul_f32 v[82:83], v[60:61], v[60:61]
	v_add_f32_e32 v70, v85, v70
	v_add_f32_e32 v70, v82, v70
	v_add_f32_e32 v70, v83, v70
	v_pk_mul_f32 v[62:63], v[62:63], v[224:225]
	v_pk_mul_f32 v[72:73], v[60:61], v[230:231]
	v_pk_mul_f32 v[60:61], v[58:59], v[228:229]
	v_pk_mul_f32 v[64:65], v[64:65], v[226:227]
	v_cvt_pk_bf16_f32 v58, v62, v63
	s_nop 0
	v_cvt_pk_bf16_f32 v59, v64, v65
	v_cvt_pk_bf16_f32 v60, v60, v61
	v_cvt_pk_bf16_f32 v61, v72, v73
	flat_store_dwordx4 v[68:69], v[58:61]
.LBB0_912:
	s_nop 0
	s_and_b64 vcc, exec, s[36:37]
	v_pk_fma_f32 v[56:57], v[56:57], v[218:219], v[242:243]
	v_pk_fma_f32 v[54:55], v[54:55], v[216:217], v[240:241]
	v_pk_fma_f32 v[52:53], v[52:53], v[222:223], v[246:247]
	v_pk_fma_f32 v[50:51], v[50:51], v[220:221], v[244:245]
	flat_store_dwordx4 v[66:67], v[54:57] offset:512
	flat_store_dwordx4 v[66:67], v[50:53] offset:528
	s_cbranch_vccnz .LBB0_914
	v_pk_mul_f32 v[72:73], v[54:55], v[54:55]
	v_pk_mul_f32 v[66:67], v[56:57], v[56:57]
	v_add_f32_e32 v71, v72, v73
	v_add_f32_e32 v66, v66, v71
	v_pk_mul_f32 v[76:77], v[50:51], v[50:51]
	v_add_f32_e32 v66, v67, v66
	v_add_f32_e32 v66, v76, v66
	v_pk_mul_f32 v[74:75], v[52:53], v[52:53]
	v_add_f32_e32 v66, v77, v66
	v_add_f32_e32 v66, v74, v66
	v_add_f32_e32 v66, v75, v66
	v_add_f32_e32 v70, v70, v66
	v_pk_mul_f32 v[54:55], v[54:55], v[232:233]
	v_pk_mul_f32 v[58:59], v[52:53], v[238:239]
	v_pk_mul_f32 v[52:53], v[50:51], v[236:237]
	v_pk_mul_f32 v[56:57], v[56:57], v[234:235]
	v_cvt_pk_bf16_f32 v50, v54, v55
	s_nop 0
	v_cvt_pk_bf16_f32 v51, v56, v57
	v_cvt_pk_bf16_f32 v52, v52, v53
	v_cvt_pk_bf16_f32 v53, v58, v59
	flat_store_dwordx4 v[68:69], v[50:53] offset:256

; DI void st8(bf16_t* p, const pg8::f32x4& v0, const pg8::f32x4& v1) { u32x4 w; w.x = cvtpk(v0[0], v0[1]); w.y = cvtpk(v0[2], v0[3]); w.z = cvtpk(v1[0], v1[1]); w.w = cvtpk(v1[2], v1[3]); *(u32x4*)p = w; }
;     DI void operator()(const pg8::f32x4 (&acc)[2][2][4][2], const pg8::Unit& u, int wr, int wc, int fr, int fq) const {
;     ...
;             for (int m = 0; m < 4; ++m) { const int rit = ai * 128 + wr * 64 + m * 16 + fr; float ss = 0.f;
;                 const size_t roff = (seg == 0 ? (size_t)(b * TC + rit) * DM : (size_t)(b * SEQ + (seg - 1) * 256 + rit) * DM);
; #pragma unroll
;                 for (int bj = 0; bj < 2; ++bj) { const int col0 = u.pn * 256 + bj * 128 + wc * 32 + 8 * fq;
;                     float* p = (seg == 0 ? xc : out) + roff + col0; const float* q = (seg == 0 ? sc : sx) + roff + col0;
;                     const pg8::f32x4 g0 = *(const pg8::f32x4*)(gbase + col0), g1 = *(const pg8::f32x4*)(gbase + col0 + 4); pg8::f32x4 x0 = *(const pg8::f32x4*)q, x1 = *(const pg8::f32x4*)(q + 4);
;                     x0 += g0 * acc[ai][bj][m][0]; x1 += g1 * acc[ai][bj][m][1]; *(pg8::f32x4*)p = x0; *(pg8::f32x4*)(p + 4) = x1;
;                     if (emit) { const pg8::f32x4 p0 = *(const pg8::f32x4*)(gpb + col0), p1 = *(const pg8::f32x4*)(gpb + col0 + 4);
;                         ss += x0[0] * x0[0] + x0[1] * x0[1] + x0[2] * x0[2] + x0[3] * x0[3] + x1[0] * x1[0] + x1[1] * x1[1] + x1[2] * x1[2] + x1[3] * x1[3];
;                         st8(H + (size_t)(u.pm * 256 + rit) * 1024 + col0, x0 * p0, x1 * p1); }
.LBB0_918:
	v_add_u32_e32 v52, 0x90, v158
	v_add_u32_e32 v50, s2, v52
	s_waitcnt lgkmcnt(0)
	v_ashrrev_i32_e32 v51, 31, v50
	v_add_u32_e32 v52, s6, v52
	v_lshlrev_b64 v[50:51], 12, v[50:51]
	v_ashrrev_i32_e32 v53, 31, v52
	v_lshl_add_u64 v[50:51], s[58:59], 0, v[50:51]
	v_lshlrev_b64 v[68:69], 11, v[52:53]
	v_lshl_add_u64 v[50:51], v[160:161], 2, v[50:51]
	flat_load_dwordx4 v[60:63], v[50:51]
	flat_load_dwordx4 v[64:67], v[50:51] offset:16
	flat_load_dwordx4 v[240:243], v[50:51] offset:512
	flat_load_dwordx4 v[244:247], v[50:51] offset:528
	s_and_b64 vcc, exec, s[36:37]
	s_waitcnt vmcnt(0) lgkmcnt(0)
	v_pk_fma_f32 v[46:47], v[46:47], v[208:209], v[60:61]
	v_lshl_add_u64 v[52:53], s[64:65], 0, v[68:69]
	v_pk_fma_f32 v[48:49], v[48:49], v[210:211], v[62:63]
	v_pk_fma_f32 v[44:45], v[44:45], v[214:215], v[66:67]
	v_pk_fma_f32 v[42:43], v[42:43], v[212:213], v[64:65]
	v_mov_b32_e32 v54, 0
	v_lshl_add_u64 v[52:53], v[160:161], 1, v[52:53]
	flat_store_dwordx4 v[50:51], v[46:49]
	flat_store_dwordx4 v[50:51], v[42:45] offset:16
	s_cbranch_vccnz .LBB0_920
	v_pk_mul_f32 v[64:65], v[46:47], v[46:47]
	v_pk_mul_f32 v[54:55], v[48:49], v[48:49]
	v_add_f32_e32 v64, v64, v65
	v_add_f32_e32 v54, v54, v64
	v_pk_mul_f32 v[68:69], v[42:43], v[42:43]
	v_add_f32_e32 v54, v55, v54
	v_add_f32_e32 v54, v68, v54
	v_pk_mul_f32 v[66:67], v[44:45], v[44:45]
	v_add_f32_e32 v54, v69, v54
	v_add_f32_e32 v54, v66, v54
	v_add_f32_e32 v54, v67, v54
	v_pk_mul_f32 v[46:47], v[46:47], v[224:225]
	v_pk_mul_f32 v[56:57], v[44:45], v[230:231]
	v_pk_mul_f32 v[44:45], v[42:43], v[228:229]
	v_pk_mul_f32 v[48:49], v[48:49], v[226:227]
	v_cvt_pk_bf16_f32 v42, v46, v47
	s_nop 0
	v_cvt_pk_bf16_f32 v43, v48, v49
	v_cvt_pk_bf16_f32 v44, v44, v45
	v_cvt_pk_bf16_f32 v45, v56, v57
	flat_store_dwordx4 v[52:53], v[42:45]
.LBB0_920:
	s_nop 0
	s_and_b64 vcc, exec, s[36:37]
	v_pk_fma_f32 v[40:41], v[40:41], v[218:219], v[242:243]
	v_pk_fma_f32 v[38:39], v[38:39], v[216:217], v[240:241]
	v_pk_fma_f32 v[36:37], v[36:37], v[222:223], v[246:247]
	v_pk_fma_f32 v[34:35], v[34:35], v[220:221], v[244:245]
	flat_store_dwordx4 v[50:51], v[38:41] offset:512
	flat_store_dwordx4 v[50:51], v[34:37] offset:528
	s_cbranch_vccnz .LBB0_922
	v_pk_mul_f32 v[56:57], v[38:39], v[38:39]
	v_pk_mul_f32 v[50:51], v[40:41], v[40:41]
	v_add_f32_e32 v55, v56, v57
	v_add_f32_e32 v50, v50, v55
	v_pk_mul_f32 v[60:61], v[34:35], v[34:35]
	v_add_f32_e32 v50, v51, v50
	v_add_f32_e32 v50, v60, v50
	v_pk_mul_f32 v[58:59], v[36:37], v[36:37]
	v_add_f32_e32 v50, v61, v50
	v_add_f32_e32 v50, v58, v50
	v_add_f32_e32 v50, v59, v50
	v_add_f32_e32 v54, v54, v50
	v_pk_mul_f32 v[38:39], v[38:39], v[232:233]
	v_pk_mul_f32 v[42:43], v[36:37], v[238:239]
	v_pk_mul_f32 v[36:37], v[34:35], v[236:237]
	v_pk_mul_f32 v[40:41], v[40:41], v[234:235]
	v_cvt_pk_bf16_f32 v34, v38, v39
	s_nop 0
	v_cvt_pk_bf16_f32 v35, v40, v41
	v_cvt_pk_bf16_f32 v36, v36, v37
	v_cvt_pk_bf16_f32 v37, v42, v43
	flat_store_dwordx4 v[52:53], v[34:37] offset:256

; DI void st8(bf16_t* p, const pg8::f32x4& v0, const pg8::f32x4& v1) { u32x4 w; w.x = cvtpk(v0[0], v0[1]); w.y = cvtpk(v0[2], v0[3]); w.z = cvtpk(v1[0], v1[1]); w.w = cvtpk(v1[2], v1[3]); *(u32x4*)p = w; }
;     DI void operator()(const pg8::f32x4 (&acc)[2][2][4][2], const pg8::Unit& u, int wr, int wc, int fr, int fq) const {
;     ...
;             for (int m = 0; m < 4; ++m) { const int rit = ai * 128 + wr * 64 + m * 16 + fr; float ss = 0.f;
;                 const size_t roff = (seg == 0 ? (size_t)(b * TC + rit) * DM : (size_t)(b * SEQ + (seg - 1) * 256 + rit) * DM);
; #pragma unroll
;                 for (int bj = 0; bj < 2; ++bj) { const int col0 = u.pn * 256 + bj * 128 + wc * 32 + 8 * fq;
;                     float* p = (seg == 0 ? xc : out) + roff + col0; const float* q = (seg == 0 ? sc : sx) + roff + col0;
;                     const pg8::f32x4 g0 = *(const pg8::f32x4*)(gbase + col0), g1 = *(const pg8::f32x4*)(gbase + col0 + 4); pg8::f32x4 x0 = *(const pg8::f32x4*)q, x1 = *(const pg8::f32x4*)(q + 4);
;                     x0 += g0 * acc[ai][bj][m][0]; x1 += g1 * acc[ai][bj][m][1]; *(pg8::f32x4*)p = x0; *(pg8::f32x4*)(p + 4) = x1;
;                     if (emit) { const pg8::f32x4 p0 = *(const pg8::f32x4*)(gpb + col0), p1 = *(const pg8::f32x4*)(gpb + col0 + 4);
;                         ss += x0[0] * x0[0] + x0[1] * x0[1] + x0[2] * x0[2] + x0[3] * x0[3] + x1[0] * x1[0] + x1[1] * x1[1] + x1[2] * x1[2] + x1[3] * x1[3];
;                         st8(H + (size_t)(u.pm * 256 + rit) * 1024 + col0, x0 * p0, x1 * p1); }
.LBB0_926:
	v_add_u32_e32 v36, 0xa0, v158
	v_add_u32_e32 v34, s2, v36
	s_waitcnt lgkmcnt(0)
	v_ashrrev_i32_e32 v35, 31, v34
	v_add_u32_e32 v36, s6, v36
	v_lshlrev_b64 v[34:35], 12, v[34:35]
	v_ashrrev_i32_e32 v37, 31, v36
	v_lshl_add_u64 v[34:35], s[58:59], 0, v[34:35]
	v_lshlrev_b64 v[52:53], 11, v[36:37]
	v_lshl_add_u64 v[34:35], v[160:161], 2, v[34:35]
	flat_load_dwordx4 v[44:47], v[34:35]
	flat_load_dwordx4 v[48:51], v[34:35] offset:16
	flat_load_dwordx4 v[240:243], v[34:35] offset:512
	flat_load_dwordx4 v[244:247], v[34:35] offset:528
	s_and_b64 vcc, exec, s[36:37]
	s_waitcnt vmcnt(0) lgkmcnt(0)
	v_pk_fma_f32 v[30:31], v[30:31], v[208:209], v[44:45]
	v_lshl_add_u64 v[36:37], s[64:65], 0, v[52:53]
	v_pk_fma_f32 v[32:33], v[32:33], v[210:211], v[46:47]
	v_pk_fma_f32 v[28:29], v[28:29], v[214:215], v[50:51]
	v_pk_fma_f32 v[26:27], v[26:27], v[212:213], v[48:49]
	v_mov_b32_e32 v38, 0
	v_lshl_add_u64 v[36:37], v[160:161], 1, v[36:37]
	flat_store_dwordx4 v[34:35], v[30:33]
	flat_store_dwordx4 v[34:35], v[26:29] offset:16
	s_cbranch_vccnz .LBB0_928
	v_pk_mul_f32 v[48:49], v[30:31], v[30:31]
	v_pk_mul_f32 v[38:39], v[32:33], v[32:33]
	v_add_f32_e32 v48, v48, v49
	v_add_f32_e32 v38, v38, v48
	v_pk_mul_f32 v[52:53], v[26:27], v[26:27]
	v_add_f32_e32 v38, v39, v38
	v_add_f32_e32 v38, v52, v38
	v_pk_mul_f32 v[50:51], v[28:29], v[28:29]
	v_add_f32_e32 v38, v53, v38
	v_add_f32_e32 v38, v50, v38
	v_add_f32_e32 v38, v51, v38
	v_pk_mul_f32 v[30:31], v[30:31], v[224:225]
	v_pk_mul_f32 v[40:41], v[28:29], v[230:231]
	v_pk_mul_f32 v[28:29], v[26:27], v[228:229]
	v_pk_mul_f32 v[32:33], v[32:33], v[226:227]
	v_cvt_pk_bf16_f32 v26, v30, v31
	s_nop 0
	v_cvt_pk_bf16_f32 v27, v32, v33
	v_cvt_pk_bf16_f32 v28, v28, v29
	v_cvt_pk_bf16_f32 v29, v40, v41
	flat_store_dwordx4 v[36:37], v[26:29]
.LBB0_928:
	s_nop 0
	s_and_b64 vcc, exec, s[36:37]
	v_pk_fma_f32 v[24:25], v[24:25], v[218:219], v[242:243]
	v_pk_fma_f32 v[22:23], v[22:23], v[216:217], v[240:241]
	v_pk_fma_f32 v[20:21], v[20:21], v[222:223], v[246:247]
	v_pk_fma_f32 v[18:19], v[18:19], v[220:221], v[244:245]
	flat_store_dwordx4 v[34:35], v[22:25] offset:512
	flat_store_dwordx4 v[34:35], v[18:21] offset:528
	s_cbranch_vccnz .LBB0_930
	v_pk_mul_f32 v[40:41], v[22:23], v[22:23]
	v_pk_mul_f32 v[34:35], v[24:25], v[24:25]
	v_add_f32_e32 v39, v40, v41
	v_add_f32_e32 v34, v34, v39
	v_pk_mul_f32 v[44:45], v[18:19], v[18:19]
	v_add_f32_e32 v34, v35, v34
	v_add_f32_e32 v34, v44, v34
	v_pk_mul_f32 v[42:43], v[20:21], v[20:21]
	v_add_f32_e32 v34, v45, v34
	v_add_f32_e32 v34, v42, v34
	v_add_f32_e32 v34, v43, v34
	v_add_f32_e32 v38, v38, v34
	v_pk_mul_f32 v[22:23], v[22:23], v[232:233]
	v_pk_mul_f32 v[26:27], v[20:21], v[238:239]
	v_pk_mul_f32 v[20:21], v[18:19], v[236:237]
	v_pk_mul_f32 v[24:25], v[24:25], v[234:235]
	v_cvt_pk_bf16_f32 v18, v22, v23
	s_nop 0
	v_cvt_pk_bf16_f32 v19, v24, v25
	v_cvt_pk_bf16_f32 v20, v20, v21
	v_cvt_pk_bf16_f32 v21, v26, v27
	flat_store_dwordx4 v[36:37], v[18:21] offset:256

; DI void st8(bf16_t* p, const pg8::f32x4& v0, const pg8::f32x4& v1) { u32x4 w; w.x = cvtpk(v0[0], v0[1]); w.y = cvtpk(v0[2], v0[3]); w.z = cvtpk(v1[0], v1[1]); w.w = cvtpk(v1[2], v1[3]); *(u32x4*)p = w; }
;     DI void operator()(const pg8::f32x4 (&acc)[2][2][4][2], const pg8::Unit& u, int wr, int wc, int fr, int fq) const {
;     ...
;             for (int m = 0; m < 4; ++m) { const int rit = ai * 128 + wr * 64 + m * 16 + fr; float ss = 0.f;
;                 const size_t roff = (seg == 0 ? (size_t)(b * TC + rit) * DM : (size_t)(b * SEQ + (seg - 1) * 256 + rit) * DM);
; #pragma unroll
;                 for (int bj = 0; bj < 2; ++bj) { const int col0 = u.pn * 256 + bj * 128 + wc * 32 + 8 * fq;
;                     float* p = (seg == 0 ? xc : out) + roff + col0; const float* q = (seg == 0 ? sc : sx) + roff + col0;
;                     const pg8::f32x4 g0 = *(const pg8::f32x4*)(gbase + col0), g1 = *(const pg8::f32x4*)(gbase + col0 + 4); pg8::f32x4 x0 = *(const pg8::f32x4*)q, x1 = *(const pg8::f32x4*)(q + 4);
;                     x0 += g0 * acc[ai][bj][m][0]; x1 += g1 * acc[ai][bj][m][1]; *(pg8::f32x4*)p = x0; *(pg8::f32x4*)(p + 4) = x1;
;                     if (emit) { const pg8::f32x4 p0 = *(const pg8::f32x4*)(gpb + col0), p1 = *(const pg8::f32x4*)(gpb + col0 + 4);
;                         ss += x0[0] * x0[0] + x0[1] * x0[1] + x0[2] * x0[2] + x0[3] * x0[3] + x1[0] * x1[0] + x1[1] * x1[1] + x1[2] * x1[2] + x1[3] * x1[3];
;                         st8(H + (size_t)(u.pm * 256 + rit) * 1024 + col0, x0 * p0, x1 * p1); }
.LBB0_934:
	v_add_u32_e32 v20, 0xb0, v158
	v_add_u32_e32 v18, s2, v20
	s_waitcnt lgkmcnt(0)
	v_ashrrev_i32_e32 v19, 31, v18
	v_add_u32_e32 v20, s6, v20
	v_lshlrev_b64 v[18:19], 12, v[18:19]
	v_ashrrev_i32_e32 v21, 31, v20
	v_lshl_add_u64 v[18:19], s[58:59], 0, v[18:19]
	v_lshlrev_b64 v[36:37], 11, v[20:21]
	v_lshl_add_u64 v[18:19], v[160:161], 2, v[18:19]
	flat_load_dwordx4 v[28:31], v[18:19]
	flat_load_dwordx4 v[32:35], v[18:19] offset:16
	flat_load_dwordx4 v[240:243], v[18:19] offset:512
	flat_load_dwordx4 v[244:247], v[18:19] offset:528
	s_and_b64 vcc, exec, s[36:37]
	s_waitcnt vmcnt(0) lgkmcnt(0)
	v_pk_fma_f32 v[14:15], v[14:15], v[208:209], v[28:29]
	v_lshl_add_u64 v[20:21], s[64:65], 0, v[36:37]
	v_pk_fma_f32 v[16:17], v[16:17], v[210:211], v[30:31]
	v_pk_fma_f32 v[12:13], v[12:13], v[214:215], v[34:35]
	v_pk_fma_f32 v[10:11], v[10:11], v[212:213], v[32:33]
	v_mov_b32_e32 v22, 0
	v_lshl_add_u64 v[20:21], v[160:161], 1, v[20:21]
	flat_store_dwordx4 v[18:19], v[14:17]
	flat_store_dwordx4 v[18:19], v[10:13] offset:16
	s_cbranch_vccnz .LBB0_936
	v_pk_mul_f32 v[32:33], v[14:15], v[14:15]
	v_pk_mul_f32 v[22:23], v[16:17], v[16:17]
	v_add_f32_e32 v32, v32, v33
	v_add_f32_e32 v22, v22, v32
	v_pk_mul_f32 v[36:37], v[10:11], v[10:11]
	v_add_f32_e32 v22, v23, v22
	v_add_f32_e32 v22, v36, v22
	v_pk_mul_f32 v[34:35], v[12:13], v[12:13]
	v_add_f32_e32 v22, v37, v22
	v_add_f32_e32 v22, v34, v22
	v_add_f32_e32 v22, v35, v22
	v_pk_mul_f32 v[14:15], v[14:15], v[224:225]
	v_pk_mul_f32 v[24:25], v[12:13], v[230:231]
	v_pk_mul_f32 v[12:13], v[10:11], v[228:229]
	v_pk_mul_f32 v[16:17], v[16:17], v[226:227]
	v_cvt_pk_bf16_f32 v10, v14, v15
	s_nop 0
	v_cvt_pk_bf16_f32 v11, v16, v17
	v_cvt_pk_bf16_f32 v12, v12, v13
	v_cvt_pk_bf16_f32 v13, v24, v25
	flat_store_dwordx4 v[20:21], v[10:13]
.LBB0_936:
	s_nop 0
	s_and_b64 vcc, exec, s[36:37]
	v_pk_fma_f32 v[8:9], v[8:9], v[218:219], v[242:243]
	v_pk_fma_f32 v[6:7], v[6:7], v[216:217], v[240:241]
	v_pk_fma_f32 v[4:5], v[4:5], v[222:223], v[246:247]
	v_pk_fma_f32 v[2:3], v[2:3], v[220:221], v[244:245]
	flat_store_dwordx4 v[18:19], v[6:9] offset:512
	flat_store_dwordx4 v[18:19], v[2:5] offset:528
	s_cbranch_vccnz .LBB0_938
	v_pk_mul_f32 v[24:25], v[6:7], v[6:7]
	v_pk_mul_f32 v[18:19], v[8:9], v[8:9]
	v_add_f32_e32 v23, v24, v25
	v_add_f32_e32 v18, v18, v23
	v_pk_mul_f32 v[28:29], v[2:3], v[2:3]
	v_add_f32_e32 v18, v19, v18
	v_add_f32_e32 v18, v28, v18
	v_pk_mul_f32 v[26:27], v[4:5], v[4:5]
	v_add_f32_e32 v18, v29, v18
	v_add_f32_e32 v18, v26, v18
	v_add_f32_e32 v18, v27, v18
	v_add_f32_e32 v22, v22, v18
	v_pk_mul_f32 v[6:7], v[6:7], v[232:233]
	v_pk_mul_f32 v[10:11], v[4:5], v[238:239]
	v_pk_mul_f32 v[4:5], v[2:3], v[236:237]
	v_pk_mul_f32 v[8:9], v[8:9], v[234:235]
	v_cvt_pk_bf16_f32 v2, v6, v7
	s_nop 0
	v_cvt_pk_bf16_f32 v3, v8, v9
	v_cvt_pk_bf16_f32 v4, v4, v5
	v_cvt_pk_bf16_f32 v5, v10, v11
	flat_store_dwordx4 v[20:21], v[2:5] offset:256

; #define PG8_BAR __builtin_amdgcn_s_barrier()
; template <class Epi, class Sched, bool ALIGN_EPI = false, bool SP2 = false>
; __device__ __forceinline__ void gemm_phase(PG8_LAS unsigned char* lds, const Gemm g, const Sched& S, const Epi& E) {
;     ...
;         if (!has_next) break;
; #pragma unroll
;         for (int a = 0; a < 2; ++a)
; #pragma unroll
;             for (int b = 0; b < 2; ++b)
; #pragma unroll
;                 for (int m = 0; m < 4; ++m)
; #pragma unroll
;                     for (int n = 0; n < 2; ++n) acc[a][b][m][n] = (f32x4){0.f, 0.f, 0.f, 0.f};
;         cur = nxt; cA = nA; cB = nB; ++ui;
;         if constexpr (ALIGN_EPI) { if (wr == 1) PG8_BAR; }
;     }
.LBB0_942:
	s_andn2_b64 vcc, exec, s[0:1]
	s_mov_b64 s[0:1], -1
	s_cbranch_vccnz .LBB0_869
	v_readlane_b32 s0, v252, 36
	v_readlane_b32 s1, v252, 37
	s_andn2_b64 vcc, exec, s[0:1]
	s_cbranch_vccnz .LBB0_868
	s_barrier
	s_branch .LBB0_868
	s_nop 0
	s_nop 0
	s_nop 0
	s_nop 0
	s_nop 0
	s_nop 0
	s_nop 0
	s_nop 0

; DI void st8(bf16_t* p, const pg8::f32x4& v0, const pg8::f32x4& v1) { u32x4 w; w.x = cvtpk(v0[0], v0[1]); w.y = cvtpk(v0[2], v0[3]); w.z = cvtpk(v1[0], v1[1]); w.w = cvtpk(v1[2], v1[3]); *(u32x4*)p = w; }
;     DI void operator()(const pg8::f32x4 (&acc)[2][2][4][2], const pg8::Unit& u, int wr, int wc, int fr, int fq) const {
;     ...
;         const int b = u.pm / 9, seg = u.pm - b * 9, mrow = seg == 0 ? 32 : b;
;         const float* gbase = mods + (size_t)mrow * 6144 + gidx * 1024; const float* gpb = gp + (size_t)mrow * 1024;
; #pragma unroll
;         for (int ai = 0; ai < 2; ++ai)
; #pragma unroll
;             for (int m = 0; m < 4; ++m) { const int rit = ai * 128 + wr * 64 + m * 16 + fr; float ss = 0.f;
;                 const size_t roff = (seg == 0 ? (size_t)(b * TC + rit) * DM : (size_t)(b * SEQ + (seg - 1) * 256 + rit) * DM);
; #pragma unroll
;                 for (int bj = 0; bj < 2; ++bj) { const int col0 = u.pn * 256 + bj * 128 + wc * 32 + 8 * fq;
;                     float* p = (seg == 0 ? xc : out) + roff + col0; const float* q = (seg == 0 ? sc : sx) + roff + col0;
;                     const pg8::f32x4 g0 = *(const pg8::f32x4*)(gbase + col0), g1 = *(const pg8::f32x4*)(gbase + col0 + 4); pg8::f32x4 x0 = *(const pg8::f32x4*)q, x1 = *(const pg8::f32x4*)(q + 4);
;                     x0 += g0 * acc[ai][bj][m][0]; x1 += g1 * acc[ai][bj][m][1]; *(pg8::f32x4*)p = x0; *(pg8::f32x4*)(p + 4) = x1;
;                     if (emit) { const pg8::f32x4 p0 = *(const pg8::f32x4*)(gpb + col0), p1 = *(const pg8::f32x4*)(gpb + col0 + 4);
;                         ss += x0[0] * x0[0] + x0[1] * x0[1] + x0[2] * x0[2] + x0[3] * x0[3] + x1[0] * x1[0] + x1[1] * x1[1] + x1[2] * x1[2] + x1[3] * x1[3];
;                         st8(H + (size_t)(u.pm * 256 + rit) * 1024 + col0, x0 * p0, x1 * p1); }
;                     __builtin_amdgcn_sched_barrier(0); }
;                 if (emit) { ss += __shfl_xor(ss, 16, 64); ss += __shfl_xor(ss, 32, 64); if (fq == 0) atomicAdd(rs + u.pm * 256 + rit, ss); }
.LBB0_992:
	s_mul_hi_i32 s4, s36, 0x38e38e39
	s_lshr_b32 s5, s4, 31
	s_ashr_i32 s4, s4, 1
	s_add_i32 s4, s4, s5
	s_mul_i32 s5, s4, -9
	s_add_i32 s5, s5, s36
	s_cmp_eq_u32 s5, 0
	s_cselect_b64 s[50:51], -1, 0
	s_and_b64 s[58:59], s[50:51], exec
	s_cselect_b32 s58, 32, s4
	s_ashr_i32 s59, s58, 31
	s_mul_i32 s21, s58, 0x6000
	s_mul_hi_i32 s14, s58, 0x6000
	s_add_u32 s21, s79, s21
	s_addc_u32 s14, s82, s14
	s_add_u32 s70, s21, 0x2000
	s_addc_u32 s71, s14, 0
	s_lshl_b64 s[58:59], s[58:59], 12
	s_add_u32 vcc_lo, s55, s58
	s_addc_u32 vcc_hi, s96, s59
	s_lshl_b32 s14, s20, 8
	v_mov_b32_e32 v157, v0
	v_mov_b32_e32 v152, v166
	s_or_b32 s14, s14, s33
	s_lshl_b32 s5, s5, 8
	v_lshl_add_u32 v158, v157, 3, s14
	s_lshl_b32 s14, s4, 11
	s_lshl_b32 s20, s36, 8
	s_add_i32 s5, s14, s5
	s_addk_i32 s5, 0xff00
	s_lshl_b32 s4, s4, 8
	s_ashr_i32 s21, s20, 31
	s_and_b64 s[36:37], s[50:51], exec
	v_add_u32_e32 v156, s97, v152
	s_cselect_b32 s57, s4, s5
	v_add_u32_e32 v152, s57, v156
	v_ashrrev_i32_e32 v153, 31, v152
	v_lshlrev_b64 v[152:153], 12, v[152:153]
	v_ashrrev_i32_e32 v159, 31, v158
	s_cselect_b32 s59, s91, s89
	s_cselect_b32 s58, s54, s90
	v_lshlrev_b64 v[162:163], 2, v[158:159]
	v_lshl_add_u64 v[160:161], s[58:59], 0, v[152:153]
	v_lshl_add_u64 v[170:171], v[160:161], 0, v[162:163]
	v_lshl_add_u64 v[164:165], s[70:71], 0, v[162:163]
	flat_load_dwordx4 v[188:191], v[170:171]
	flat_load_dwordx4 v[208:211], v[164:165]
	flat_load_dwordx4 v[212:215], v[164:165] offset:16
	flat_load_dwordx4 v[200:203], v[170:171] offset:16
	flat_load_dwordx4 v[240:243], v[170:171] offset:512
	flat_load_dwordx4 v[244:247], v[170:171] offset:528
	s_cselect_b32 s61, s88, s63
	s_cselect_b32 s60, s83, s62
	v_lshl_add_u64 v[152:153], s[60:61], 0, v[152:153]
	v_lshl_add_u64 v[152:153], v[152:153], 0, v[162:163]
	v_lshl_add_u64 v[160:161], vcc, 0, v[162:163]
	v_cmp_eq_u32_e32 vcc, 0, v157
	flat_load_dwordx4 v[216:219], v[164:165] offset:512
	flat_load_dwordx4 v[220:223], v[164:165] offset:528
	flat_load_dwordx4 v[224:227], v[160:161]
	flat_load_dwordx4 v[228:231], v[160:161] offset:16
	flat_load_dwordx4 v[232:235], v[160:161] offset:512
	flat_load_dwordx4 v[236:239], v[160:161] offset:528
	s_waitcnt vmcnt(0) lgkmcnt(0)
	v_pk_fma_f32 v[128:129], v[128:129], v[210:211], v[190:191]
	v_pk_fma_f32 v[126:127], v[126:127], v[208:209], v[188:189]
	v_pk_fma_f32 v[124:125], v[124:125], v[214:215], v[202:203]
	v_pk_fma_f32 v[122:123], v[122:123], v[212:213], v[200:201]
	flat_store_dwordx4 v[152:153], v[126:129]
	flat_store_dwordx4 v[152:153], v[122:125] offset:16
	v_mul_f32_e32 v157, v127, v127
	v_fmac_f32_e32 v157, v126, v126
	v_fmac_f32_e32 v157, v128, v128
	v_add_u32_e32 v196, s20, v156
	v_fmac_f32_e32 v157, v129, v129
	v_ashrrev_i32_e32 v197, 31, v196
	v_fmac_f32_e32 v157, v122, v122
	v_lshlrev_b64 v[196:197], 11, v[196:197]
	v_fmac_f32_e32 v157, v123, v123
	v_lshl_add_u64 v[196:197], s[38:39], 0, v[196:197]
	v_fmac_f32_e32 v157, v124, v124
	v_lshl_add_u64 v[200:201], v[158:159], 1, v[196:197]
	v_fmac_f32_e32 v157, v125, v125
	v_pk_mul_f32 v[126:127], v[126:127], v[224:225]
	v_pk_mul_f32 v[188:189], v[124:125], v[230:231]
	v_pk_mul_f32 v[124:125], v[122:123], v[228:229]
	v_pk_mul_f32 v[128:129], v[128:129], v[226:227]
	v_cvt_pk_bf16_f32 v122, v126, v127
	s_nop 0
	v_cvt_pk_bf16_f32 v123, v128, v129
	v_cvt_pk_bf16_f32 v124, v124, v125
	v_cvt_pk_bf16_f32 v125, v188, v189
	flat_store_dwordx4 v[200:201], v[122:125]
	s_nop 1
	v_add_u32_e32 v122, 0x80, v158
	v_ashrrev_i32_e32 v123, 31, v122
	v_lshl_add_u64 v[122:123], v[122:123], 2, s[70:71]
	v_pk_fma_f32 v[120:121], v[120:121], v[218:219], v[242:243]
	v_pk_fma_f32 v[118:119], v[118:119], v[216:217], v[240:241]
	v_pk_fma_f32 v[116:117], v[116:117], v[222:223], v[246:247]
	v_pk_fma_f32 v[114:115], v[114:115], v[220:221], v[244:245]
	flat_store_dwordx4 v[152:153], v[118:121] offset:512
	flat_store_dwordx4 v[152:153], v[114:117] offset:528
	v_mul_f32_e32 v128, v119, v119
	v_fmac_f32_e32 v128, v118, v118
	v_fmac_f32_e32 v128, v120, v120
	v_fmac_f32_e32 v128, v121, v121
	v_fmac_f32_e32 v128, v114, v114
	v_fmac_f32_e32 v128, v115, v115
	v_fmac_f32_e32 v128, v116, v116
	v_fmac_f32_e32 v128, v117, v117
	v_add_f32_e32 v128, v157, v128
	v_pk_mul_f32 v[118:119], v[118:119], v[232:233]
	v_pk_mul_f32 v[124:125], v[116:117], v[238:239]
	v_pk_mul_f32 v[116:117], v[114:115], v[236:237]
	v_pk_mul_f32 v[120:121], v[120:121], v[234:235]
	v_cvt_pk_bf16_f32 v114, v118, v119
	s_nop 0
	v_cvt_pk_bf16_f32 v115, v120, v121
	v_cvt_pk_bf16_f32 v116, v116, v117
	v_cvt_pk_bf16_f32 v117, v124, v125
	flat_store_dwordx4 v[200:201], v[114:117] offset:256
	v_cmp_lt_i32_e64 s[36:37], v181, v176
	v_ashrrev_i32_e32 v157, 31, v156
	s_nop 0
	v_cndmask_b32_e64 v114, v174, v181, s[36:37]
	v_lshlrev_b32_e32 v114, 2, v114
	ds_bpermute_b32 v115, v114, v128
	v_cmp_lt_i32_e64 s[36:37], v182, v176
	s_waitcnt lgkmcnt(0)
	v_add_f32_e32 v116, v128, v115
	v_cndmask_b32_e64 v117, v174, v182, s[36:37]
	v_lshlrev_b32_e32 v115, 2, v117
	ds_bpermute_b32 v117, v115, v116
	s_and_saveexec_b64 s[36:37], vcc
	s_cbranch_execz .LBB0_994
	s_lshl_b64 s[50:51], s[20:21], 2
	s_add_u32 s50, s80, s50
	s_addc_u32 s51, s81, s51
	v_lshl_add_u64 v[118:119], v[156:157], 2, s[50:51]
	s_waitcnt lgkmcnt(0)
	v_add_f32_e32 v116, v116, v117
	flat_atomic_add_f32 v[118:119], v116
; DI void st8(bf16_t* p, const pg8::f32x4& v0, const pg8::f32x4& v1) { u32x4 w; w.x = cvtpk(v0[0], v0[1]); w.y = cvtpk(v0[2], v0[3]); w.z = cvtpk(v1[0], v1[1]); w.w = cvtpk(v1[2], v1[3]); *(u32x4*)p = w; }
;     DI void operator()(const pg8::f32x4 (&acc)[2][2][4][2], const pg8::Unit& u, int wr, int wc, int fr, int fq) const {
;     ...
;             for (int m = 0; m < 4; ++m) { const int rit = ai * 128 + wr * 64 + m * 16 + fr; float ss = 0.f;
;                 const size_t roff = (seg == 0 ? (size_t)(b * TC + rit) * DM : (size_t)(b * SEQ + (seg - 1) * 256 + rit) * DM);
; #pragma unroll
;                 for (int bj = 0; bj < 2; ++bj) { const int col0 = u.pn * 256 + bj * 128 + wc * 32 + 8 * fq;
;                     float* p = (seg == 0 ? xc : out) + roff + col0; const float* q = (seg == 0 ? sc : sx) + roff + col0;
;                     const pg8::f32x4 g0 = *(const pg8::f32x4*)(gbase + col0), g1 = *(const pg8::f32x4*)(gbase + col0 + 4); pg8::f32x4 x0 = *(const pg8::f32x4*)q, x1 = *(const pg8::f32x4*)(q + 4);
;                     x0 += g0 * acc[ai][bj][m][0]; x1 += g1 * acc[ai][bj][m][1]; *(pg8::f32x4*)p = x0; *(pg8::f32x4*)(p + 4) = x1;
;                     if (emit) { const pg8::f32x4 p0 = *(const pg8::f32x4*)(gpb + col0), p1 = *(const pg8::f32x4*)(gpb + col0 + 4);
;                         ss += x0[0] * x0[0] + x0[1] * x0[1] + x0[2] * x0[2] + x0[3] * x0[3] + x1[0] * x1[0] + x1[1] * x1[1] + x1[2] * x1[2] + x1[3] * x1[3];
;                         st8(H + (size_t)(u.pm * 256 + rit) * 1024 + col0, x0 * p0, x1 * p1); }
;                     __builtin_amdgcn_sched_barrier(0); }
;                 if (emit) { ss += __shfl_xor(ss, 16, 64); ss += __shfl_xor(ss, 32, 64); if (fq == 0) atomicAdd(rs + u.pm * 256 + rit, ss); }
.LBB0_994:
	s_or_b64 exec, exec, s[36:37]
	v_add_u32_e32 v152, 16, v156
	v_add_u32_e32 v116, s57, v152
	s_waitcnt lgkmcnt(0)
	v_ashrrev_i32_e32 v117, 31, v116
	v_lshlrev_b64 v[120:121], 12, v[116:117]
	v_lshl_add_u64 v[116:117], s[58:59], 0, v[120:121]
	v_lshl_add_u64 v[128:129], v[116:117], 0, v[162:163]
	flat_load_dwordx4 v[116:119], v[128:129]
	flat_load_dwordx4 v[192:195], v[128:129] offset:16
	flat_load_dwordx4 v[240:243], v[128:129] offset:512
	flat_load_dwordx4 v[244:247], v[128:129] offset:528
	v_lshl_add_u64 v[120:121], s[60:61], 0, v[120:121]
	v_lshl_add_u64 v[120:121], v[120:121], 0, v[162:163]
	v_add_u32_e32 v152, s20, v152
	v_ashrrev_i32_e32 v153, 31, v152
	v_lshlrev_b64 v[152:153], 11, v[152:153]
	v_lshl_add_u64 v[152:153], s[38:39], 0, v[152:153]
	v_lshl_add_u64 v[152:153], v[158:159], 1, v[152:153]
	s_waitcnt vmcnt(0) lgkmcnt(0)
	v_pk_fma_f32 v[112:113], v[112:113], v[210:211], v[118:119]
	v_pk_fma_f32 v[110:111], v[110:111], v[208:209], v[116:117]
	v_pk_fma_f32 v[108:109], v[108:109], v[214:215], v[194:195]
	v_pk_fma_f32 v[106:107], v[106:107], v[212:213], v[192:193]
	flat_store_dwordx4 v[120:121], v[110:113]
	flat_store_dwordx4 v[120:121], v[106:109] offset:16
	v_mul_f32_e32 v169, v111, v111
	v_fmac_f32_e32 v169, v110, v110
	v_fmac_f32_e32 v169, v112, v112
	v_fmac_f32_e32 v169, v113, v113
	v_fmac_f32_e32 v169, v106, v106
	v_fmac_f32_e32 v169, v107, v107
	v_fmac_f32_e32 v169, v108, v108
	v_fmac_f32_e32 v169, v109, v109
	v_pk_mul_f32 v[110:111], v[110:111], v[224:225]
	v_pk_mul_f32 v[116:117], v[108:109], v[230:231]
	v_pk_mul_f32 v[108:109], v[106:107], v[228:229]
	v_pk_mul_f32 v[112:113], v[112:113], v[226:227]
	v_cvt_pk_bf16_f32 v106, v110, v111
	s_nop 0
	v_cvt_pk_bf16_f32 v107, v112, v113
	v_cvt_pk_bf16_f32 v108, v108, v109
	v_cvt_pk_bf16_f32 v109, v116, v117
	flat_store_dwordx4 v[152:153], v[106:109]
	s_nop 0
	v_pk_fma_f32 v[104:105], v[104:105], v[218:219], v[242:243]
	v_pk_fma_f32 v[102:103], v[102:103], v[216:217], v[240:241]
	v_pk_fma_f32 v[100:101], v[100:101], v[222:223], v[246:247]
	v_pk_fma_f32 v[98:99], v[98:99], v[220:221], v[244:245]
	flat_store_dwordx4 v[120:121], v[102:105] offset:512
	flat_store_dwordx4 v[120:121], v[98:101] offset:528
	v_mul_f32_e32 v116, v103, v103
	v_fmac_f32_e32 v116, v102, v102
	v_fmac_f32_e32 v116, v104, v104
	v_fmac_f32_e32 v116, v105, v105
	v_fmac_f32_e32 v116, v98, v98
	v_fmac_f32_e32 v116, v99, v99
	v_fmac_f32_e32 v116, v100, v100
	v_fmac_f32_e32 v116, v101, v101
	v_add_f32_e32 v116, v169, v116
	v_pk_mul_f32 v[102:103], v[102:103], v[232:233]
	v_pk_mul_f32 v[106:107], v[100:101], v[238:239]
	v_pk_mul_f32 v[100:101], v[98:99], v[236:237]
	v_pk_mul_f32 v[104:105], v[104:105], v[234:235]
	v_cvt_pk_bf16_f32 v98, v102, v103
	s_nop 0
	v_cvt_pk_bf16_f32 v99, v104, v105
	v_cvt_pk_bf16_f32 v100, v100, v101
	v_cvt_pk_bf16_f32 v101, v106, v107
	flat_store_dwordx4 v[152:153], v[98:101] offset:256
	ds_bpermute_b32 v98, v114, v116
	s_waitcnt lgkmcnt(0)
	v_add_f32_e32 v98, v116, v98
	ds_bpermute_b32 v99, v115, v98
	s_and_saveexec_b64 s[36:37], vcc
	s_cbranch_execz .LBB0_996
	s_lshl_b64 s[50:51], s[20:21], 2
	s_add_u32 s50, s80, s50
	s_addc_u32 s51, s81, s51
	v_lshl_add_u64 v[100:101], v[156:157], 2, s[50:51]
	s_waitcnt lgkmcnt(0)
	v_add_f32_e32 v98, v98, v99
	flat_atomic_add_f32 v[100:101], v98 offset:64
.LBB0_996:
	s_or_b64 exec, exec, s[36:37]
	v_add_u32_e32 v120, 32, v156
	v_add_u32_e32 v98, s57, v120
	s_waitcnt lgkmcnt(0)
	v_ashrrev_i32_e32 v99, 31, v98
	v_lshlrev_b64 v[116:117], 12, v[98:99]
	v_lshl_add_u64 v[98:99], s[58:59], 0, v[116:117]
	v_lshl_add_u64 v[118:119], v[98:99], 0, v[162:163]
	flat_load_dwordx4 v[98:101], v[118:119]
	flat_load_dwordx4 v[110:113], v[118:119] offset:16
	flat_load_dwordx4 v[240:243], v[118:119] offset:512
	flat_load_dwordx4 v[244:247], v[118:119] offset:528
	v_lshl_add_u64 v[116:117], s[60:61], 0, v[116:117]
	v_lshl_add_u64 v[116:117], v[116:117], 0, v[162:163]
	s_waitcnt vmcnt(0) lgkmcnt(0)
	v_pk_fma_f32 v[96:97], v[96:97], v[210:211], v[100:101]
	v_pk_fma_f32 v[94:95], v[94:95], v[208:209], v[98:99]
	v_pk_fma_f32 v[92:93], v[92:93], v[214:215], v[112:113]
	v_pk_fma_f32 v[90:91], v[90:91], v[212:213], v[110:111]
	flat_store_dwordx4 v[116:117], v[94:97]
	flat_store_dwordx4 v[116:117], v[90:93] offset:16
	v_mul_f32_e32 v108, v95, v95
	v_fmac_f32_e32 v108, v94, v94
	v_fmac_f32_e32 v108, v96, v96
	v_add_u32_e32 v106, s20, v120
	v_fmac_f32_e32 v108, v97, v97
	v_ashrrev_i32_e32 v107, 31, v106
	v_fmac_f32_e32 v108, v90, v90
	v_lshlrev_b64 v[106:107], 11, v[106:107]
	v_fmac_f32_e32 v108, v91, v91
	v_lshl_add_u64 v[106:107], s[38:39], 0, v[106:107]
	v_fmac_f32_e32 v108, v92, v92
	v_lshl_add_u64 v[106:107], v[158:159], 1, v[106:107]
	v_fmac_f32_e32 v108, v93, v93
	v_pk_mul_f32 v[94:95], v[94:95], v[224:225]
	v_pk_mul_f32 v[98:99], v[92:93], v[230:231]
	v_pk_mul_f32 v[92:93], v[90:91], v[228:229]
	v_pk_mul_f32 v[96:97], v[96:97], v[226:227]
	v_cvt_pk_bf16_f32 v90, v94, v95
	s_nop 0
	v_cvt_pk_bf16_f32 v91, v96, v97
	v_cvt_pk_bf16_f32 v92, v92, v93
	v_cvt_pk_bf16_f32 v93, v98, v99
	flat_store_dwordx4 v[106:107], v[90:93]
	s_nop 0
	v_pk_fma_f32 v[88:89], v[88:89], v[218:219], v[242:243]
	v_pk_fma_f32 v[86:87], v[86:87], v[216:217], v[240:241]
	v_pk_fma_f32 v[84:85], v[84:85], v[222:223], v[246:247]
	v_pk_fma_f32 v[82:83], v[82:83], v[220:221], v[244:245]
	flat_store_dwordx4 v[116:117], v[86:89] offset:512
	flat_store_dwordx4 v[116:117], v[82:85] offset:528
	v_mul_f32_e32 v98, v87, v87
	v_fmac_f32_e32 v98, v86, v86
	v_fmac_f32_e32 v98, v88, v88
	v_fmac_f32_e32 v98, v89, v89
	v_fmac_f32_e32 v98, v82, v82
	v_fmac_f32_e32 v98, v83, v83
	v_fmac_f32_e32 v98, v84, v84
	v_fmac_f32_e32 v98, v85, v85
	v_add_f32_e32 v98, v108, v98
	v_pk_mul_f32 v[86:87], v[86:87], v[232:233]
	v_pk_mul_f32 v[90:91], v[84:85], v[238:239]
	v_pk_mul_f32 v[84:85], v[82:83], v[236:237]
	v_pk_mul_f32 v[88:89], v[88:89], v[234:235]
	v_cvt_pk_bf16_f32 v82, v86, v87
	s_nop 0
	v_cvt_pk_bf16_f32 v83, v88, v89
	v_cvt_pk_bf16_f32 v84, v84, v85
	v_cvt_pk_bf16_f32 v85, v90, v91
	flat_store_dwordx4 v[106:107], v[82:85] offset:256
	ds_bpermute_b32 v82, v114, v98
	s_waitcnt lgkmcnt(0)
	v_add_f32_e32 v82, v98, v82
	ds_bpermute_b32 v83, v115, v82
	s_and_saveexec_b64 s[36:37], vcc
	s_cbranch_execz .LBB0_998
	s_lshl_b64 s[50:51], s[20:21], 2
	s_add_u32 s50, s80, s50
	s_addc_u32 s51, s81, s51
	v_lshl_add_u64 v[84:85], v[156:157], 2, s[50:51]
	s_waitcnt lgkmcnt(0)
	v_add_f32_e32 v82, v82, v83
	flat_atomic_add_f32 v[84:85], v82 offset:128
; DI void st8(bf16_t* p, const pg8::f32x4& v0, const pg8::f32x4& v1) { u32x4 w; w.x = cvtpk(v0[0], v0[1]); w.y = cvtpk(v0[2], v0[3]); w.z = cvtpk(v1[0], v1[1]); w.w = cvtpk(v1[2], v1[3]); *(u32x4*)p = w; }
;     DI void operator()(const pg8::f32x4 (&acc)[2][2][4][2], const pg8::Unit& u, int wr, int wc, int fr, int fq) const {
;     ...
;             for (int m = 0; m < 4; ++m) { const int rit = ai * 128 + wr * 64 + m * 16 + fr; float ss = 0.f;
;                 const size_t roff = (seg == 0 ? (size_t)(b * TC + rit) * DM : (size_t)(b * SEQ + (seg - 1) * 256 + rit) * DM);
; #pragma unroll
;                 for (int bj = 0; bj < 2; ++bj) { const int col0 = u.pn * 256 + bj * 128 + wc * 32 + 8 * fq;
;                     float* p = (seg == 0 ? xc : out) + roff + col0; const float* q = (seg == 0 ? sc : sx) + roff + col0;
;                     const pg8::f32x4 g0 = *(const pg8::f32x4*)(gbase + col0), g1 = *(const pg8::f32x4*)(gbase + col0 + 4); pg8::f32x4 x0 = *(const pg8::f32x4*)q, x1 = *(const pg8::f32x4*)(q + 4);
;                     x0 += g0 * acc[ai][bj][m][0]; x1 += g1 * acc[ai][bj][m][1]; *(pg8::f32x4*)p = x0; *(pg8::f32x4*)(p + 4) = x1;
;                     if (emit) { const pg8::f32x4 p0 = *(const pg8::f32x4*)(gpb + col0), p1 = *(const pg8::f32x4*)(gpb + col0 + 4);
;                         ss += x0[0] * x0[0] + x0[1] * x0[1] + x0[2] * x0[2] + x0[3] * x0[3] + x1[0] * x1[0] + x1[1] * x1[1] + x1[2] * x1[2] + x1[3] * x1[3];
;                         st8(H + (size_t)(u.pm * 256 + rit) * 1024 + col0, x0 * p0, x1 * p1); }
;                     __builtin_amdgcn_sched_barrier(0); }
;                 if (emit) { ss += __shfl_xor(ss, 16, 64); ss += __shfl_xor(ss, 32, 64); if (fq == 0) atomicAdd(rs + u.pm * 256 + rit, ss); }
.LBB0_998:
	s_or_b64 exec, exec, s[36:37]
	v_add_u32_e32 v102, 48, v156
	v_add_u32_e32 v82, s57, v102
	s_waitcnt lgkmcnt(0)
	v_ashrrev_i32_e32 v83, 31, v82
	v_lshlrev_b64 v[98:99], 12, v[82:83]
	v_lshl_add_u64 v[82:83], s[58:59], 0, v[98:99]
	v_lshl_add_u64 v[100:101], v[82:83], 0, v[162:163]
	flat_load_dwordx4 v[82:85], v[100:101]
	flat_load_dwordx4 v[94:97], v[100:101] offset:16
	flat_load_dwordx4 v[240:243], v[100:101] offset:512
	flat_load_dwordx4 v[244:247], v[100:101] offset:528
	v_lshl_add_u64 v[98:99], s[60:61], 0, v[98:99]
	v_lshl_add_u64 v[98:99], v[98:99], 0, v[162:163]
	s_waitcnt vmcnt(0) lgkmcnt(0)
	v_pk_fma_f32 v[80:81], v[80:81], v[210:211], v[84:85]
	v_pk_fma_f32 v[78:79], v[78:79], v[208:209], v[82:83]
	v_pk_fma_f32 v[76:77], v[76:77], v[214:215], v[96:97]
	v_pk_fma_f32 v[74:75], v[74:75], v[212:213], v[94:95]
	flat_store_dwordx4 v[98:99], v[78:81]
	flat_store_dwordx4 v[98:99], v[74:77] offset:16
	v_mul_f32_e32 v92, v79, v79
	v_fmac_f32_e32 v92, v78, v78
	v_fmac_f32_e32 v92, v80, v80
	v_add_u32_e32 v90, s20, v102
	v_fmac_f32_e32 v92, v81, v81
	v_ashrrev_i32_e32 v91, 31, v90
	v_fmac_f32_e32 v92, v74, v74
	v_lshlrev_b64 v[90:91], 11, v[90:91]
	v_fmac_f32_e32 v92, v75, v75
	v_lshl_add_u64 v[90:91], s[38:39], 0, v[90:91]
	v_fmac_f32_e32 v92, v76, v76
	v_lshl_add_u64 v[90:91], v[158:159], 1, v[90:91]
	v_fmac_f32_e32 v92, v77, v77
	v_pk_mul_f32 v[78:79], v[78:79], v[224:225]
	v_pk_mul_f32 v[82:83], v[76:77], v[230:231]
	v_pk_mul_f32 v[76:77], v[74:75], v[228:229]
	v_pk_mul_f32 v[80:81], v[80:81], v[226:227]
	v_cvt_pk_bf16_f32 v74, v78, v79
	s_nop 0
	v_cvt_pk_bf16_f32 v75, v80, v81
	v_cvt_pk_bf16_f32 v76, v76, v77
	v_cvt_pk_bf16_f32 v77, v82, v83
	flat_store_dwordx4 v[90:91], v[74:77]
	s_nop 0
	v_pk_fma_f32 v[72:73], v[72:73], v[218:219], v[242:243]
	v_pk_fma_f32 v[70:71], v[70:71], v[216:217], v[240:241]
	v_pk_fma_f32 v[68:69], v[68:69], v[222:223], v[246:247]
	v_pk_fma_f32 v[66:67], v[66:67], v[220:221], v[244:245]
	flat_store_dwordx4 v[98:99], v[70:73] offset:512
	flat_store_dwordx4 v[98:99], v[66:69] offset:528
	v_mul_f32_e32 v82, v71, v71
	v_fmac_f32_e32 v82, v70, v70
	v_fmac_f32_e32 v82, v72, v72
	v_fmac_f32_e32 v82, v73, v73
	v_fmac_f32_e32 v82, v66, v66
	v_fmac_f32_e32 v82, v67, v67
	v_fmac_f32_e32 v82, v68, v68
	v_fmac_f32_e32 v82, v69, v69
	v_add_f32_e32 v82, v92, v82
	v_pk_mul_f32 v[70:71], v[70:71], v[232:233]
	v_pk_mul_f32 v[74:75], v[68:69], v[238:239]
	v_pk_mul_f32 v[68:69], v[66:67], v[236:237]
	v_pk_mul_f32 v[72:73], v[72:73], v[234:235]
	v_cvt_pk_bf16_f32 v66, v70, v71
	s_nop 0
	v_cvt_pk_bf16_f32 v67, v72, v73
	v_cvt_pk_bf16_f32 v68, v68, v69
	v_cvt_pk_bf16_f32 v69, v74, v75
	flat_store_dwordx4 v[90:91], v[66:69] offset:256
	ds_bpermute_b32 v66, v114, v82
	s_waitcnt lgkmcnt(0)
	v_add_f32_e32 v66, v82, v66
	ds_bpermute_b32 v67, v115, v66
	s_and_saveexec_b64 s[36:37], vcc
	s_cbranch_execz .LBB0_1000
	s_lshl_b64 s[50:51], s[20:21], 2
	s_add_u32 s50, s80, s50
	s_addc_u32 s51, s81, s51
	v_lshl_add_u64 v[68:69], v[156:157], 2, s[50:51]
	s_waitcnt lgkmcnt(0)
	v_add_f32_e32 v66, v66, v67
	flat_atomic_add_f32 v[68:69], v66 offset:192
.LBB0_1000:
	s_or_b64 exec, exec, s[36:37]
	v_add_u32_e32 v86, 0x80, v156
	v_add_u32_e32 v66, s57, v86
	s_waitcnt lgkmcnt(0)
	v_ashrrev_i32_e32 v67, 31, v66
	v_lshlrev_b64 v[82:83], 12, v[66:67]
	v_lshl_add_u64 v[66:67], s[58:59], 0, v[82:83]
	v_lshl_add_u64 v[84:85], v[66:67], 0, v[162:163]
	flat_load_dwordx4 v[66:69], v[84:85]
	flat_load_dwordx4 v[78:81], v[84:85] offset:16
	flat_load_dwordx4 v[240:243], v[84:85] offset:512
	flat_load_dwordx4 v[244:247], v[84:85] offset:528
	v_lshl_add_u64 v[82:83], s[60:61], 0, v[82:83]
	v_lshl_add_u64 v[82:83], v[82:83], 0, v[162:163]
	s_waitcnt vmcnt(0) lgkmcnt(0)
	v_pk_fma_f32 v[64:65], v[64:65], v[210:211], v[68:69]
	v_pk_fma_f32 v[62:63], v[62:63], v[208:209], v[66:67]
	v_pk_fma_f32 v[60:61], v[60:61], v[214:215], v[80:81]
	v_pk_fma_f32 v[58:59], v[58:59], v[212:213], v[78:79]
	flat_store_dwordx4 v[82:83], v[62:65]
	flat_store_dwordx4 v[82:83], v[58:61] offset:16
	v_mul_f32_e32 v76, v63, v63
	v_fmac_f32_e32 v76, v62, v62
	v_fmac_f32_e32 v76, v64, v64
	v_add_u32_e32 v74, s20, v86
	v_fmac_f32_e32 v76, v65, v65
	v_ashrrev_i32_e32 v75, 31, v74
	v_fmac_f32_e32 v76, v58, v58
	v_lshlrev_b64 v[74:75], 11, v[74:75]
	v_fmac_f32_e32 v76, v59, v59
	v_lshl_add_u64 v[74:75], s[38:39], 0, v[74:75]
	v_fmac_f32_e32 v76, v60, v60
	v_lshl_add_u64 v[74:75], v[158:159], 1, v[74:75]
	v_fmac_f32_e32 v76, v61, v61
	v_pk_mul_f32 v[62:63], v[62:63], v[224:225]
	v_pk_mul_f32 v[66:67], v[60:61], v[230:231]
	v_pk_mul_f32 v[60:61], v[58:59], v[228:229]
	v_pk_mul_f32 v[64:65], v[64:65], v[226:227]
	v_cvt_pk_bf16_f32 v58, v62, v63
	s_nop 0
	v_cvt_pk_bf16_f32 v59, v64, v65
	v_cvt_pk_bf16_f32 v60, v60, v61
	v_cvt_pk_bf16_f32 v61, v66, v67
	flat_store_dwordx4 v[74:75], v[58:61]
	s_nop 0
	v_pk_fma_f32 v[56:57], v[56:57], v[218:219], v[242:243]
	v_pk_fma_f32 v[54:55], v[54:55], v[216:217], v[240:241]
	v_pk_fma_f32 v[52:53], v[52:53], v[222:223], v[246:247]
	v_pk_fma_f32 v[50:51], v[50:51], v[220:221], v[244:245]
	flat_store_dwordx4 v[82:83], v[54:57] offset:512
	flat_store_dwordx4 v[82:83], v[50:53] offset:528
	v_mul_f32_e32 v66, v55, v55
	v_fmac_f32_e32 v66, v54, v54
	v_fmac_f32_e32 v66, v56, v56
	v_fmac_f32_e32 v66, v57, v57
	v_fmac_f32_e32 v66, v50, v50
	v_fmac_f32_e32 v66, v51, v51
	v_fmac_f32_e32 v66, v52, v52
	v_fmac_f32_e32 v66, v53, v53
	v_add_f32_e32 v66, v76, v66
	v_pk_mul_f32 v[54:55], v[54:55], v[232:233]
	v_pk_mul_f32 v[58:59], v[52:53], v[238:239]
	v_pk_mul_f32 v[52:53], v[50:51], v[236:237]
	v_pk_mul_f32 v[56:57], v[56:57], v[234:235]
	v_cvt_pk_bf16_f32 v50, v54, v55
	s_nop 0
	v_cvt_pk_bf16_f32 v51, v56, v57
	v_cvt_pk_bf16_f32 v52, v52, v53
	v_cvt_pk_bf16_f32 v53, v58, v59
	flat_store_dwordx4 v[74:75], v[50:53] offset:256
	ds_bpermute_b32 v50, v114, v66
	s_waitcnt lgkmcnt(0)
	v_add_f32_e32 v50, v66, v50
	ds_bpermute_b32 v51, v115, v50
	s_and_saveexec_b64 s[36:37], vcc
	s_cbranch_execz .LBB0_1002
	s_lshl_b64 s[50:51], s[20:21], 2
	s_add_u32 s50, s80, s50
	s_addc_u32 s51, s81, s51
	v_lshl_add_u64 v[52:53], v[156:157], 2, s[50:51]
	s_waitcnt lgkmcnt(0)
	v_add_f32_e32 v50, v50, v51
	flat_atomic_add_f32 v[52:53], v50 offset:512
; DI void st8(bf16_t* p, const pg8::f32x4& v0, const pg8::f32x4& v1) { u32x4 w; w.x = cvtpk(v0[0], v0[1]); w.y = cvtpk(v0[2], v0[3]); w.z = cvtpk(v1[0], v1[1]); w.w = cvtpk(v1[2], v1[3]); *(u32x4*)p = w; }
;     DI void operator()(const pg8::f32x4 (&acc)[2][2][4][2], const pg8::Unit& u, int wr, int wc, int fr, int fq) const {
;     ...
;             for (int m = 0; m < 4; ++m) { const int rit = ai * 128 + wr * 64 + m * 16 + fr; float ss = 0.f;
;                 const size_t roff = (seg == 0 ? (size_t)(b * TC + rit) * DM : (size_t)(b * SEQ + (seg - 1) * 256 + rit) * DM);
; #pragma unroll
;                 for (int bj = 0; bj < 2; ++bj) { const int col0 = u.pn * 256 + bj * 128 + wc * 32 + 8 * fq;
;                     float* p = (seg == 0 ? xc : out) + roff + col0; const float* q = (seg == 0 ? sc : sx) + roff + col0;
;                     const pg8::f32x4 g0 = *(const pg8::f32x4*)(gbase + col0), g1 = *(const pg8::f32x4*)(gbase + col0 + 4); pg8::f32x4 x0 = *(const pg8::f32x4*)q, x1 = *(const pg8::f32x4*)(q + 4);
;                     x0 += g0 * acc[ai][bj][m][0]; x1 += g1 * acc[ai][bj][m][1]; *(pg8::f32x4*)p = x0; *(pg8::f32x4*)(p + 4) = x1;
;                     if (emit) { const pg8::f32x4 p0 = *(const pg8::f32x4*)(gpb + col0), p1 = *(const pg8::f32x4*)(gpb + col0 + 4);
;                         ss += x0[0] * x0[0] + x0[1] * x0[1] + x0[2] * x0[2] + x0[3] * x0[3] + x1[0] * x1[0] + x1[1] * x1[1] + x1[2] * x1[2] + x1[3] * x1[3];
;                         st8(H + (size_t)(u.pm * 256 + rit) * 1024 + col0, x0 * p0, x1 * p1); }
;                     __builtin_amdgcn_sched_barrier(0); }
;                 if (emit) { ss += __shfl_xor(ss, 16, 64); ss += __shfl_xor(ss, 32, 64); if (fq == 0) atomicAdd(rs + u.pm * 256 + rit, ss); }
.LBB0_1002:
	s_or_b64 exec, exec, s[36:37]
	v_add_u32_e32 v70, 0x90, v156
	v_add_u32_e32 v50, s57, v70
	s_waitcnt lgkmcnt(0)
	v_ashrrev_i32_e32 v51, 31, v50
	v_lshlrev_b64 v[66:67], 12, v[50:51]
	v_lshl_add_u64 v[50:51], s[58:59], 0, v[66:67]
	v_lshl_add_u64 v[68:69], v[50:51], 0, v[162:163]
	flat_load_dwordx4 v[50:53], v[68:69]
	flat_load_dwordx4 v[62:65], v[68:69] offset:16
	flat_load_dwordx4 v[240:243], v[68:69] offset:512
	flat_load_dwordx4 v[244:247], v[68:69] offset:528
	v_lshl_add_u64 v[66:67], s[60:61], 0, v[66:67]
	v_lshl_add_u64 v[66:67], v[66:67], 0, v[162:163]
	s_waitcnt vmcnt(0) lgkmcnt(0)
	v_pk_fma_f32 v[48:49], v[48:49], v[210:211], v[52:53]
	v_pk_fma_f32 v[46:47], v[46:47], v[208:209], v[50:51]
	v_pk_fma_f32 v[44:45], v[44:45], v[214:215], v[64:65]
	v_pk_fma_f32 v[42:43], v[42:43], v[212:213], v[62:63]
	flat_store_dwordx4 v[66:67], v[46:49]
	flat_store_dwordx4 v[66:67], v[42:45] offset:16
	v_mul_f32_e32 v60, v47, v47
	v_fmac_f32_e32 v60, v46, v46
	v_fmac_f32_e32 v60, v48, v48
	v_add_u32_e32 v58, s20, v70
	v_fmac_f32_e32 v60, v49, v49
	v_ashrrev_i32_e32 v59, 31, v58
	v_fmac_f32_e32 v60, v42, v42
	v_lshlrev_b64 v[58:59], 11, v[58:59]
	v_fmac_f32_e32 v60, v43, v43
	v_lshl_add_u64 v[58:59], s[38:39], 0, v[58:59]
	v_fmac_f32_e32 v60, v44, v44
	v_lshl_add_u64 v[58:59], v[158:159], 1, v[58:59]
	v_fmac_f32_e32 v60, v45, v45
	v_pk_mul_f32 v[46:47], v[46:47], v[224:225]
	v_pk_mul_f32 v[50:51], v[44:45], v[230:231]
	v_pk_mul_f32 v[44:45], v[42:43], v[228:229]
	v_pk_mul_f32 v[48:49], v[48:49], v[226:227]
	v_cvt_pk_bf16_f32 v42, v46, v47
	s_nop 0
	v_cvt_pk_bf16_f32 v43, v48, v49
	v_cvt_pk_bf16_f32 v44, v44, v45
	v_cvt_pk_bf16_f32 v45, v50, v51
	flat_store_dwordx4 v[58:59], v[42:45]
	s_nop 0
	v_pk_fma_f32 v[40:41], v[40:41], v[218:219], v[242:243]
	v_pk_fma_f32 v[38:39], v[38:39], v[216:217], v[240:241]
	v_pk_fma_f32 v[36:37], v[36:37], v[222:223], v[246:247]
	v_pk_fma_f32 v[34:35], v[34:35], v[220:221], v[244:245]
	flat_store_dwordx4 v[66:67], v[38:41] offset:512
	flat_store_dwordx4 v[66:67], v[34:37] offset:528
	v_mul_f32_e32 v50, v39, v39
	v_fmac_f32_e32 v50, v38, v38
	v_fmac_f32_e32 v50, v40, v40
	v_fmac_f32_e32 v50, v41, v41
	v_fmac_f32_e32 v50, v34, v34
	v_fmac_f32_e32 v50, v35, v35
	v_fmac_f32_e32 v50, v36, v36
	v_fmac_f32_e32 v50, v37, v37
	v_add_f32_e32 v50, v60, v50
	v_pk_mul_f32 v[38:39], v[38:39], v[232:233]
	v_pk_mul_f32 v[42:43], v[36:37], v[238:239]
	v_pk_mul_f32 v[36:37], v[34:35], v[236:237]
	v_pk_mul_f32 v[40:41], v[40:41], v[234:235]
	v_cvt_pk_bf16_f32 v34, v38, v39
	s_nop 0
	v_cvt_pk_bf16_f32 v35, v40, v41
	v_cvt_pk_bf16_f32 v36, v36, v37
	v_cvt_pk_bf16_f32 v37, v42, v43
	flat_store_dwordx4 v[58:59], v[34:37] offset:256
	ds_bpermute_b32 v34, v114, v50
	s_waitcnt lgkmcnt(0)
	v_add_f32_e32 v34, v50, v34
	ds_bpermute_b32 v35, v115, v34
	s_and_saveexec_b64 s[36:37], vcc
	s_cbranch_execz .LBB0_1004
	s_lshl_b64 s[50:51], s[20:21], 2
	s_add_u32 s50, s80, s50
	s_addc_u32 s51, s81, s51
	v_lshl_add_u64 v[36:37], v[156:157], 2, s[50:51]
	s_waitcnt lgkmcnt(0)
	v_add_f32_e32 v34, v34, v35
	flat_atomic_add_f32 v[36:37], v34 offset:576
.LBB0_1004:
	s_or_b64 exec, exec, s[36:37]
	v_add_u32_e32 v54, 0xa0, v156
	v_add_u32_e32 v34, s57, v54
	s_waitcnt lgkmcnt(0)
	v_ashrrev_i32_e32 v35, 31, v34
	v_lshlrev_b64 v[50:51], 12, v[34:35]
	v_lshl_add_u64 v[34:35], s[58:59], 0, v[50:51]
	v_lshl_add_u64 v[52:53], v[34:35], 0, v[162:163]
	flat_load_dwordx4 v[34:37], v[52:53]
	flat_load_dwordx4 v[46:49], v[52:53] offset:16
	flat_load_dwordx4 v[240:243], v[52:53] offset:512
	flat_load_dwordx4 v[244:247], v[52:53] offset:528
	v_lshl_add_u64 v[50:51], s[60:61], 0, v[50:51]
	v_lshl_add_u64 v[50:51], v[50:51], 0, v[162:163]
	s_waitcnt vmcnt(0) lgkmcnt(0)
	v_pk_fma_f32 v[32:33], v[32:33], v[210:211], v[36:37]
	v_pk_fma_f32 v[30:31], v[30:31], v[208:209], v[34:35]
	v_pk_fma_f32 v[28:29], v[28:29], v[214:215], v[48:49]
	v_pk_fma_f32 v[26:27], v[26:27], v[212:213], v[46:47]
	flat_store_dwordx4 v[50:51], v[30:33]
	flat_store_dwordx4 v[50:51], v[26:29] offset:16
	v_mul_f32_e32 v44, v31, v31
	v_fmac_f32_e32 v44, v30, v30
	v_fmac_f32_e32 v44, v32, v32
	v_add_u32_e32 v42, s20, v54
	v_fmac_f32_e32 v44, v33, v33
	v_ashrrev_i32_e32 v43, 31, v42
	v_fmac_f32_e32 v44, v26, v26
	v_lshlrev_b64 v[42:43], 11, v[42:43]
	v_fmac_f32_e32 v44, v27, v27
	v_lshl_add_u64 v[42:43], s[38:39], 0, v[42:43]
	v_fmac_f32_e32 v44, v28, v28
	v_lshl_add_u64 v[42:43], v[158:159], 1, v[42:43]
	v_fmac_f32_e32 v44, v29, v29
	v_pk_mul_f32 v[30:31], v[30:31], v[224:225]
	v_pk_mul_f32 v[34:35], v[28:29], v[230:231]
	v_pk_mul_f32 v[28:29], v[26:27], v[228:229]
	v_pk_mul_f32 v[32:33], v[32:33], v[226:227]
	v_cvt_pk_bf16_f32 v26, v30, v31
	s_nop 0
	v_cvt_pk_bf16_f32 v27, v32, v33
	v_cvt_pk_bf16_f32 v28, v28, v29
	v_cvt_pk_bf16_f32 v29, v34, v35
	flat_store_dwordx4 v[42:43], v[26:29]
	s_nop 0
	v_pk_fma_f32 v[24:25], v[24:25], v[218:219], v[242:243]
	v_pk_fma_f32 v[22:23], v[22:23], v[216:217], v[240:241]
	v_pk_fma_f32 v[20:21], v[20:21], v[222:223], v[246:247]
	v_pk_fma_f32 v[18:19], v[18:19], v[220:221], v[244:245]
	flat_store_dwordx4 v[50:51], v[22:25] offset:512
	flat_store_dwordx4 v[50:51], v[18:21] offset:528
	v_mul_f32_e32 v34, v23, v23
	v_fmac_f32_e32 v34, v22, v22
	v_fmac_f32_e32 v34, v24, v24
	v_fmac_f32_e32 v34, v25, v25
	v_fmac_f32_e32 v34, v18, v18
	v_fmac_f32_e32 v34, v19, v19
	v_fmac_f32_e32 v34, v20, v20
	v_fmac_f32_e32 v34, v21, v21
	v_add_f32_e32 v34, v44, v34
	v_pk_mul_f32 v[22:23], v[22:23], v[232:233]
	v_pk_mul_f32 v[26:27], v[20:21], v[238:239]
	v_pk_mul_f32 v[20:21], v[18:19], v[236:237]
	v_pk_mul_f32 v[24:25], v[24:25], v[234:235]
	v_cvt_pk_bf16_f32 v18, v22, v23
	s_nop 0
	v_cvt_pk_bf16_f32 v19, v24, v25
	v_cvt_pk_bf16_f32 v20, v20, v21
	v_cvt_pk_bf16_f32 v21, v26, v27
	flat_store_dwordx4 v[42:43], v[18:21] offset:256
	ds_bpermute_b32 v18, v114, v34
	s_waitcnt lgkmcnt(0)
	v_add_f32_e32 v18, v34, v18
	ds_bpermute_b32 v19, v115, v18
	s_and_saveexec_b64 s[36:37], vcc
	s_cbranch_execz .LBB0_1006
	s_lshl_b64 s[50:51], s[20:21], 2
	s_add_u32 s50, s80, s50
	s_addc_u32 s51, s81, s51
	v_lshl_add_u64 v[20:21], v[156:157], 2, s[50:51]
	s_waitcnt lgkmcnt(0)
	v_add_f32_e32 v18, v18, v19
	flat_atomic_add_f32 v[20:21], v18 offset:640
; #define PG8_BAR __builtin_amdgcn_s_barrier()
; template <class Epi, class Sched, bool ALIGN_EPI = false, bool SP2 = false>
; __device__ __forceinline__ void gemm_phase(PG8_LAS unsigned char* lds, const Gemm g, const Sched& S, const Epi& E) {
;     ...
;         if (!has_next) break;
; #pragma unroll
;         for (int a = 0; a < 2; ++a)
; #pragma unroll
;             for (int b = 0; b < 2; ++b)
; #pragma unroll
;                 for (int m = 0; m < 4; ++m)
; #pragma unroll
;                     for (int n = 0; n < 2; ++n) acc[a][b][m][n] = (f32x4){0.f, 0.f, 0.f, 0.f};
;         cur = nxt; cA = nA; cB = nB; ++ui;
;         if constexpr (ALIGN_EPI) { if (wr == 1) PG8_BAR; }
;     }
;     DI void operator()(const pg8::f32x4 (&acc)[2][2][4][2], const pg8::Unit& u, int wr, int wc, int fr, int fq) const {
;     ...
;             for (int m = 0; m < 4; ++m) { const int rit = ai * 128 + wr * 64 + m * 16 + fr; float ss = 0.f;
;                 const size_t roff = (seg == 0 ? (size_t)(b * TC + rit) * DM : (size_t)(b * SEQ + (seg - 1) * 256 + rit) * DM);
; #pragma unroll
;                 for (int bj = 0; bj < 2; ++bj) { const int col0 = u.pn * 256 + bj * 128 + wc * 32 + 8 * fq;
;                     float* p = (seg == 0 ? xc : out) + roff + col0; const float* q = (seg == 0 ? sc : sx) + roff + col0;
;                     const pg8::f32x4 g0 = *(const pg8::f32x4*)(gbase + col0), g1 = *(const pg8::f32x4*)(gbase + col0 + 4); pg8::f32x4 x0 = *(const pg8::f32x4*)q, x1 = *(const pg8::f32x4*)(q + 4);
;                     x0 += g0 * acc[ai][bj][m][0]; x1 += g1 * acc[ai][bj][m][1]; *(pg8::f32x4*)p = x0; *(pg8::f32x4*)(p + 4) = x1;
;                     if (emit) { const pg8::f32x4 p0 = *(const pg8::f32x4*)(gpb + col0), p1 = *(const pg8::f32x4*)(gpb + col0 + 4);
;                         ss += x0[0] * x0[0] + x0[1] * x0[1] + x0[2] * x0[2] + x0[3] * x0[3] + x1[0] * x1[0] + x1[1] * x1[1] + x1[2] * x1[2] + x1[3] * x1[3];
;                         st8(H + (size_t)(u.pm * 256 + rit) * 1024 + col0, x0 * p0, x1 * p1); }
;                     __builtin_amdgcn_sched_barrier(0); }
;                 if (emit) { ss += __shfl_xor(ss, 16, 64); ss += __shfl_xor(ss, 32, 64); if (fq == 0) atomicAdd(rs + u.pm * 256 + rit, ss); }
.LBB0_1006:
	s_or_b64 exec, exec, s[36:37]
	v_add_u32_e32 v38, 0xb0, v156
	v_add_u32_e32 v18, s57, v38
	s_waitcnt lgkmcnt(0)
	v_ashrrev_i32_e32 v19, 31, v18
	v_lshlrev_b64 v[34:35], 12, v[18:19]
	v_lshl_add_u64 v[18:19], s[58:59], 0, v[34:35]
	v_lshl_add_u64 v[36:37], v[18:19], 0, v[162:163]
	flat_load_dwordx4 v[18:21], v[36:37]
	flat_load_dwordx4 v[30:33], v[36:37] offset:16
	flat_load_dwordx4 v[240:243], v[36:37] offset:512
	flat_load_dwordx4 v[244:247], v[36:37] offset:528
	v_lshl_add_u64 v[34:35], s[60:61], 0, v[34:35]
	v_lshl_add_u64 v[34:35], v[34:35], 0, v[162:163]
	s_waitcnt vmcnt(0) lgkmcnt(0)
	v_pk_fma_f32 v[16:17], v[16:17], v[210:211], v[20:21]
	v_pk_fma_f32 v[14:15], v[14:15], v[208:209], v[18:19]
	v_pk_fma_f32 v[12:13], v[12:13], v[214:215], v[32:33]
	v_pk_fma_f32 v[10:11], v[10:11], v[212:213], v[30:31]
	flat_store_dwordx4 v[34:35], v[14:17]
	flat_store_dwordx4 v[34:35], v[10:13] offset:16
	v_mul_f32_e32 v28, v15, v15
	v_fmac_f32_e32 v28, v14, v14
	v_fmac_f32_e32 v28, v16, v16
	v_add_u32_e32 v26, s20, v38
	v_fmac_f32_e32 v28, v17, v17
	v_ashrrev_i32_e32 v27, 31, v26
	v_fmac_f32_e32 v28, v10, v10
	v_lshlrev_b64 v[26:27], 11, v[26:27]
	v_fmac_f32_e32 v28, v11, v11
	v_lshl_add_u64 v[26:27], s[38:39], 0, v[26:27]
	v_fmac_f32_e32 v28, v12, v12
	v_lshl_add_u64 v[26:27], v[158:159], 1, v[26:27]
	v_fmac_f32_e32 v28, v13, v13
	v_pk_mul_f32 v[14:15], v[14:15], v[224:225]
	v_pk_mul_f32 v[18:19], v[12:13], v[230:231]
	v_pk_mul_f32 v[12:13], v[10:11], v[228:229]
	v_pk_mul_f32 v[16:17], v[16:17], v[226:227]
	v_cvt_pk_bf16_f32 v10, v14, v15
	s_nop 0
	v_cvt_pk_bf16_f32 v11, v16, v17
	v_cvt_pk_bf16_f32 v12, v12, v13
	v_cvt_pk_bf16_f32 v13, v18, v19
	flat_store_dwordx4 v[26:27], v[10:13]
	s_nop 0
	v_pk_fma_f32 v[8:9], v[8:9], v[218:219], v[242:243]
	v_pk_fma_f32 v[6:7], v[6:7], v[216:217], v[240:241]
	v_pk_fma_f32 v[4:5], v[4:5], v[222:223], v[246:247]
	v_pk_fma_f32 v[2:3], v[2:3], v[220:221], v[244:245]
	flat_store_dwordx4 v[34:35], v[6:9] offset:512
	flat_store_dwordx4 v[34:35], v[2:5] offset:528
	v_mul_f32_e32 v18, v7, v7
	v_fmac_f32_e32 v18, v6, v6
	v_fmac_f32_e32 v18, v8, v8
	v_fmac_f32_e32 v18, v9, v9
	v_fmac_f32_e32 v18, v2, v2
	v_fmac_f32_e32 v18, v3, v3
	v_fmac_f32_e32 v18, v4, v4
	v_fmac_f32_e32 v18, v5, v5
	v_add_f32_e32 v18, v28, v18
	v_pk_mul_f32 v[6:7], v[6:7], v[232:233]
	v_pk_mul_f32 v[10:11], v[4:5], v[238:239]
	v_pk_mul_f32 v[4:5], v[2:3], v[236:237]
	v_pk_mul_f32 v[8:9], v[8:9], v[234:235]
	v_cvt_pk_bf16_f32 v2, v6, v7
	s_nop 0
	v_cvt_pk_bf16_f32 v3, v8, v9
	v_cvt_pk_bf16_f32 v4, v4, v5
	v_cvt_pk_bf16_f32 v5, v10, v11
	flat_store_dwordx4 v[26:27], v[2:5] offset:256
	ds_bpermute_b32 v2, v114, v18
	s_waitcnt lgkmcnt(0)
	v_add_f32_e32 v2, v18, v2
	ds_bpermute_b32 v3, v115, v2
	s_and_saveexec_b64 s[36:37], vcc
	s_cbranch_execz .LBB0_1008
	s_lshl_b64 s[20:21], s[20:21], 2
	s_add_u32 s20, s80, s20
	s_addc_u32 s21, s81, s21
	v_lshl_add_u64 v[4:5], v[156:157], 2, s[20:21]
	s_waitcnt lgkmcnt(0)
	v_add_f32_e32 v2, v2, v3
	flat_atomic_add_f32 v[4:5], v2 offset:704
.LBB0_1008:
	s_or_b64 exec, exec, s[36:37]
	s_andn2_b64 vcc, exec, s[0:1]
	s_mov_b64 s[0:1], -1
	s_cbranch_vccnz .LBB0_983
	s_andn2_b64 vcc, exec, s[6:7]
	s_cbranch_vccnz .LBB0_982
	s_barrier
	s_branch .LBB0_982
	s_nop 0
	s_nop 0
	s_nop 0
	s_nop 0
	s_nop 0
	s_nop 0
	s_nop 0
	s_nop 0
